# GQA attention: K/V tiles staged with LDS-DMA (global_load_lds) instead of VGPR+ds_write; batched epilogues GQA/MLA/NA/GEMM_RES; GQA_POST table loads hoisted
# speedup vs baseline: 1.0617x; 1.0617x over previous
.LBB0_185:
	s_add_u32 s8, s24, s34
	s_addc_u32 s9, s25, 0
	s_add_u32 s74, s8, 0x1800
	s_addc_u32 s75, s9, 0
	s_and_b64 vcc, exec, s[6:7]
	s_cbranch_vccz .LBB0_189
	s_and_saveexec_b64 s[8:9], s[76:77]
	ds_write_b32 v134, v124 offset:32768
	s_or_b64 exec, exec, s[8:9]
	s_waitcnt lgkmcnt(0)
	v_add_u32_e32 v105, v109, v119
	ds_read_b128 v[68:71], v105 offset:32768
	ds_read_b128 v[72:75], v105 offset:32800
	ds_read_b128 v[76:79], v105 offset:32832
	ds_read_b128 v[80:83], v105 offset:32864
	v_lshl_add_u32 v104, v108, 1, v120
	v_add_u32_e32 v104, v104, v122
	s_mov_b32 s8, s74
	s_mov_b32 s9, s75
	global_load_ushort v34, v104, s[8:9] offset:0
	global_load_ushort v35, v104, s[8:9] offset:64
	s_add_u32 s8, s8, 0x2000
	s_addc_u32 s9, s9, 0
	global_load_ushort v36, v104, s[8:9] offset:0
	global_load_ushort v37, v104, s[8:9] offset:64
	s_add_u32 s8, s8, 0x2000
	s_addc_u32 s9, s9, 0
	global_load_ushort v38, v104, s[8:9] offset:0
	global_load_ushort v39, v104, s[8:9] offset:64
	s_add_u32 s8, s8, 0x2000
	s_addc_u32 s9, s9, 0
	global_load_ushort v40, v104, s[8:9] offset:0
	global_load_ushort v41, v104, s[8:9] offset:64
	s_add_u32 s8, s8, 0xa000
	s_addc_u32 s9, s9, 0
	global_load_ushort v42, v104, s[8:9] offset:0
	global_load_ushort v43, v104, s[8:9] offset:64
	s_add_u32 s8, s8, 0x2000
	s_addc_u32 s9, s9, 0
	global_load_ushort v44, v104, s[8:9] offset:0
	global_load_ushort v45, v104, s[8:9] offset:64
	s_add_u32 s8, s8, 0x2000
	s_addc_u32 s9, s9, 0
	global_load_ushort v46, v104, s[8:9] offset:0
	global_load_ushort v47, v104, s[8:9] offset:64
	s_add_u32 s8, s8, 0x2000
	s_addc_u32 s9, s9, 0
	global_load_ushort v48, v104, s[8:9] offset:0
	global_load_ushort v49, v104, s[8:9] offset:64
	s_add_u32 s8, s8, 0xa000
	s_addc_u32 s9, s9, 0
	global_load_ushort v50, v104, s[8:9] offset:0
	global_load_ushort v51, v104, s[8:9] offset:64
	s_add_u32 s8, s8, 0x2000
	s_addc_u32 s9, s9, 0
	global_load_ushort v52, v104, s[8:9] offset:0
	global_load_ushort v53, v104, s[8:9] offset:64
	s_add_u32 s8, s8, 0x2000
	s_addc_u32 s9, s9, 0
	global_load_ushort v54, v104, s[8:9] offset:0
	global_load_ushort v55, v104, s[8:9] offset:64
	s_add_u32 s8, s8, 0x2000
	s_addc_u32 s9, s9, 0
	global_load_ushort v56, v104, s[8:9] offset:0
	global_load_ushort v57, v104, s[8:9] offset:64
	s_add_u32 s8, s8, 0xa000
	s_addc_u32 s9, s9, 0
	global_load_ushort v58, v104, s[8:9] offset:0
	global_load_ushort v59, v104, s[8:9] offset:64
	s_add_u32 s8, s8, 0x2000
	s_addc_u32 s9, s9, 0
	global_load_ushort v60, v104, s[8:9] offset:0
	global_load_ushort v61, v104, s[8:9] offset:64
	s_add_u32 s8, s8, 0x2000
	s_addc_u32 s9, s9, 0
	global_load_ushort v62, v104, s[8:9] offset:0
	global_load_ushort v63, v104, s[8:9] offset:64
	s_add_u32 s8, s8, 0x2000
	s_addc_u32 s9, s9, 0
	global_load_ushort v64, v104, s[8:9] offset:0
	global_load_ushort v65, v104, s[8:9] offset:64
	s_waitcnt lgkmcnt(0)
	v_rcp_f32_e32 v84, v68
	v_rcp_f32_e32 v85, v69
	v_rcp_f32_e32 v86, v70
	v_rcp_f32_e32 v87, v71
	v_rcp_f32_e32 v88, v72
	v_rcp_f32_e32 v89, v73
	v_rcp_f32_e32 v90, v74
	v_rcp_f32_e32 v91, v75
	v_rcp_f32_e32 v92, v76
	v_rcp_f32_e32 v93, v77
	v_rcp_f32_e32 v94, v78
	v_rcp_f32_e32 v95, v79
	v_rcp_f32_e32 v96, v80
	v_rcp_f32_e32 v97, v81
	v_rcp_f32_e32 v98, v82
	v_rcp_f32_e32 v99, v83
	s_waitcnt vmcnt(30)
	v_lshlrev_b32_e32 v34, 16, v34
	v_lshlrev_b32_e32 v35, 16, v35
	v_mul_f32_e32 v100, 0xbfb8aa3b, v34
	v_mul_f32_e32 v101, 0xbfb8aa3b, v35
	v_exp_f32_e32 v100, v100
	v_exp_f32_e32 v101, v101
	v_mul_f32_e32 v102, v2, v84
	v_mul_f32_e32 v103, v18, v84
	v_add_f32_e32 v100, 1.0, v100
	v_add_f32_e32 v101, 1.0, v101
	v_rcp_f32_e32 v100, v100
	v_rcp_f32_e32 v101, v101
	s_nop 0
	v_mul_f32_e32 v34, v100, v34
	v_mul_f32_e32 v35, v101, v35
	v_mul_f32_e32 v34, v102, v34
	v_mul_f32_e32 v35, v103, v35
	v_cvt_pk_bf16_f32 v34, v34, v34
	v_cvt_pk_bf16_f32 v35, v35, v35
	s_waitcnt vmcnt(28)
	v_lshlrev_b32_e32 v36, 16, v36
	v_lshlrev_b32_e32 v37, 16, v37
	v_mul_f32_e32 v100, 0xbfb8aa3b, v36
	v_mul_f32_e32 v101, 0xbfb8aa3b, v37
	v_exp_f32_e32 v100, v100
	v_exp_f32_e32 v101, v101
	v_mul_f32_e32 v102, v3, v85
	v_mul_f32_e32 v103, v19, v85
	v_add_f32_e32 v100, 1.0, v100
	v_add_f32_e32 v101, 1.0, v101
	v_rcp_f32_e32 v100, v100
	v_rcp_f32_e32 v101, v101
	s_nop 0
	v_mul_f32_e32 v36, v100, v36
	v_mul_f32_e32 v37, v101, v37
	v_mul_f32_e32 v36, v102, v36
	v_mul_f32_e32 v37, v103, v37
	v_cvt_pk_bf16_f32 v36, v36, v36
	v_cvt_pk_bf16_f32 v37, v37, v37
	s_waitcnt vmcnt(26)
	v_lshlrev_b32_e32 v38, 16, v38
	v_lshlrev_b32_e32 v39, 16, v39
	v_mul_f32_e32 v100, 0xbfb8aa3b, v38
	v_mul_f32_e32 v101, 0xbfb8aa3b, v39
	v_exp_f32_e32 v100, v100
	v_exp_f32_e32 v101, v101
	v_mul_f32_e32 v102, v4, v86
	v_mul_f32_e32 v103, v20, v86
	v_add_f32_e32 v100, 1.0, v100
	v_add_f32_e32 v101, 1.0, v101
	v_rcp_f32_e32 v100, v100
	v_rcp_f32_e32 v101, v101
	s_nop 0
	v_mul_f32_e32 v38, v100, v38
	v_mul_f32_e32 v39, v101, v39
	v_mul_f32_e32 v38, v102, v38
	v_mul_f32_e32 v39, v103, v39
	v_cvt_pk_bf16_f32 v38, v38, v38
	v_cvt_pk_bf16_f32 v39, v39, v39
	s_waitcnt vmcnt(24)
	v_lshlrev_b32_e32 v40, 16, v40
	v_lshlrev_b32_e32 v41, 16, v41
	v_mul_f32_e32 v100, 0xbfb8aa3b, v40
	v_mul_f32_e32 v101, 0xbfb8aa3b, v41
	v_exp_f32_e32 v100, v100
	v_exp_f32_e32 v101, v101
	v_mul_f32_e32 v102, v5, v87
	v_mul_f32_e32 v103, v21, v87
	v_add_f32_e32 v100, 1.0, v100
	v_add_f32_e32 v101, 1.0, v101
	v_rcp_f32_e32 v100, v100
	v_rcp_f32_e32 v101, v101
	s_nop 0
	v_mul_f32_e32 v40, v100, v40
	v_mul_f32_e32 v41, v101, v41
	v_mul_f32_e32 v40, v102, v40
	v_mul_f32_e32 v41, v103, v41
	v_cvt_pk_bf16_f32 v40, v40, v40
	v_cvt_pk_bf16_f32 v41, v41, v41
	s_waitcnt vmcnt(22)
	v_lshlrev_b32_e32 v42, 16, v42
	v_lshlrev_b32_e32 v43, 16, v43
	v_mul_f32_e32 v100, 0xbfb8aa3b, v42
	v_mul_f32_e32 v101, 0xbfb8aa3b, v43
	v_exp_f32_e32 v100, v100
	v_exp_f32_e32 v101, v101
	v_mul_f32_e32 v102, v6, v88
	v_mul_f32_e32 v103, v22, v88
	v_add_f32_e32 v100, 1.0, v100
	v_add_f32_e32 v101, 1.0, v101
	v_rcp_f32_e32 v100, v100
	v_rcp_f32_e32 v101, v101
	s_nop 0
	v_mul_f32_e32 v42, v100, v42
	v_mul_f32_e32 v43, v101, v43
	v_mul_f32_e32 v42, v102, v42
	v_mul_f32_e32 v43, v103, v43
	v_cvt_pk_bf16_f32 v42, v42, v42
	v_cvt_pk_bf16_f32 v43, v43, v43
	s_waitcnt vmcnt(20)
	v_lshlrev_b32_e32 v44, 16, v44
	v_lshlrev_b32_e32 v45, 16, v45
	v_mul_f32_e32 v100, 0xbfb8aa3b, v44
	v_mul_f32_e32 v101, 0xbfb8aa3b, v45
	v_exp_f32_e32 v100, v100
	v_exp_f32_e32 v101, v101
	v_mul_f32_e32 v102, v7, v89
	v_mul_f32_e32 v103, v23, v89
	v_add_f32_e32 v100, 1.0, v100
	v_add_f32_e32 v101, 1.0, v101
	v_rcp_f32_e32 v100, v100
	v_rcp_f32_e32 v101, v101
	s_nop 0
	v_mul_f32_e32 v44, v100, v44
	v_mul_f32_e32 v45, v101, v45
	v_mul_f32_e32 v44, v102, v44
	v_mul_f32_e32 v45, v103, v45
	v_cvt_pk_bf16_f32 v44, v44, v44
	v_cvt_pk_bf16_f32 v45, v45, v45
	s_waitcnt vmcnt(18)
	v_lshlrev_b32_e32 v46, 16, v46
	v_lshlrev_b32_e32 v47, 16, v47
	v_mul_f32_e32 v100, 0xbfb8aa3b, v46
	v_mul_f32_e32 v101, 0xbfb8aa3b, v47
	v_exp_f32_e32 v100, v100
	v_exp_f32_e32 v101, v101
	v_mul_f32_e32 v102, v8, v90
	v_mul_f32_e32 v103, v24, v90
	v_add_f32_e32 v100, 1.0, v100
	v_add_f32_e32 v101, 1.0, v101
	v_rcp_f32_e32 v100, v100
	v_rcp_f32_e32 v101, v101
	s_nop 0
	v_mul_f32_e32 v46, v100, v46
	v_mul_f32_e32 v47, v101, v47
	v_mul_f32_e32 v46, v102, v46
	v_mul_f32_e32 v47, v103, v47
	v_cvt_pk_bf16_f32 v46, v46, v46
	v_cvt_pk_bf16_f32 v47, v47, v47
	s_waitcnt vmcnt(16)
	v_lshlrev_b32_e32 v48, 16, v48
	v_lshlrev_b32_e32 v49, 16, v49
	v_mul_f32_e32 v100, 0xbfb8aa3b, v48
	v_mul_f32_e32 v101, 0xbfb8aa3b, v49
	v_exp_f32_e32 v100, v100
	v_exp_f32_e32 v101, v101
	v_mul_f32_e32 v102, v9, v91
	v_mul_f32_e32 v103, v25, v91
	v_add_f32_e32 v100, 1.0, v100
	v_add_f32_e32 v101, 1.0, v101
	v_rcp_f32_e32 v100, v100
	v_rcp_f32_e32 v101, v101
	s_nop 0
	v_mul_f32_e32 v48, v100, v48
	v_mul_f32_e32 v49, v101, v49
	v_mul_f32_e32 v48, v102, v48
	v_mul_f32_e32 v49, v103, v49
	v_cvt_pk_bf16_f32 v48, v48, v48
	v_cvt_pk_bf16_f32 v49, v49, v49
	s_waitcnt vmcnt(14)
	v_lshlrev_b32_e32 v50, 16, v50
	v_lshlrev_b32_e32 v51, 16, v51
	v_mul_f32_e32 v100, 0xbfb8aa3b, v50
	v_mul_f32_e32 v101, 0xbfb8aa3b, v51
	v_exp_f32_e32 v100, v100
	v_exp_f32_e32 v101, v101
	v_mul_f32_e32 v102, v10, v92
	v_mul_f32_e32 v103, v26, v92
	v_add_f32_e32 v100, 1.0, v100
	v_add_f32_e32 v101, 1.0, v101
	v_rcp_f32_e32 v100, v100
	v_rcp_f32_e32 v101, v101
	s_nop 0
	v_mul_f32_e32 v50, v100, v50
	v_mul_f32_e32 v51, v101, v51
	v_mul_f32_e32 v50, v102, v50
	v_mul_f32_e32 v51, v103, v51
	v_cvt_pk_bf16_f32 v50, v50, v50
	v_cvt_pk_bf16_f32 v51, v51, v51
	s_waitcnt vmcnt(12)
	v_lshlrev_b32_e32 v52, 16, v52
	v_lshlrev_b32_e32 v53, 16, v53
	v_mul_f32_e32 v100, 0xbfb8aa3b, v52
	v_mul_f32_e32 v101, 0xbfb8aa3b, v53
	v_exp_f32_e32 v100, v100
	v_exp_f32_e32 v101, v101
	v_mul_f32_e32 v102, v11, v93
	v_mul_f32_e32 v103, v27, v93
	v_add_f32_e32 v100, 1.0, v100
	v_add_f32_e32 v101, 1.0, v101
	v_rcp_f32_e32 v100, v100
	v_rcp_f32_e32 v101, v101
	s_nop 0
	v_mul_f32_e32 v52, v100, v52
	v_mul_f32_e32 v53, v101, v53
	v_mul_f32_e32 v52, v102, v52
	v_mul_f32_e32 v53, v103, v53
	v_cvt_pk_bf16_f32 v52, v52, v52
	v_cvt_pk_bf16_f32 v53, v53, v53
	s_waitcnt vmcnt(10)
	v_lshlrev_b32_e32 v54, 16, v54
	v_lshlrev_b32_e32 v55, 16, v55
	v_mul_f32_e32 v100, 0xbfb8aa3b, v54
	v_mul_f32_e32 v101, 0xbfb8aa3b, v55
	v_exp_f32_e32 v100, v100
	v_exp_f32_e32 v101, v101
	v_mul_f32_e32 v102, v12, v94
	v_mul_f32_e32 v103, v28, v94
	v_add_f32_e32 v100, 1.0, v100
	v_add_f32_e32 v101, 1.0, v101
	v_rcp_f32_e32 v100, v100
	v_rcp_f32_e32 v101, v101
	s_nop 0
	v_mul_f32_e32 v54, v100, v54
	v_mul_f32_e32 v55, v101, v55
	v_mul_f32_e32 v54, v102, v54
	v_mul_f32_e32 v55, v103, v55
	v_cvt_pk_bf16_f32 v54, v54, v54
	v_cvt_pk_bf16_f32 v55, v55, v55
	s_waitcnt vmcnt(8)
	v_lshlrev_b32_e32 v56, 16, v56
	v_lshlrev_b32_e32 v57, 16, v57
	v_mul_f32_e32 v100, 0xbfb8aa3b, v56
	v_mul_f32_e32 v101, 0xbfb8aa3b, v57
	v_exp_f32_e32 v100, v100
	v_exp_f32_e32 v101, v101
	v_mul_f32_e32 v102, v13, v95
	v_mul_f32_e32 v103, v29, v95
	v_add_f32_e32 v100, 1.0, v100
	v_add_f32_e32 v101, 1.0, v101
	v_rcp_f32_e32 v100, v100
	v_rcp_f32_e32 v101, v101
	s_nop 0
	v_mul_f32_e32 v56, v100, v56
	v_mul_f32_e32 v57, v101, v57
	v_mul_f32_e32 v56, v102, v56
	v_mul_f32_e32 v57, v103, v57
	v_cvt_pk_bf16_f32 v56, v56, v56
	v_cvt_pk_bf16_f32 v57, v57, v57
	s_waitcnt vmcnt(6)
	v_lshlrev_b32_e32 v58, 16, v58
	v_lshlrev_b32_e32 v59, 16, v59
	v_mul_f32_e32 v100, 0xbfb8aa3b, v58
	v_mul_f32_e32 v101, 0xbfb8aa3b, v59
	v_exp_f32_e32 v100, v100
	v_exp_f32_e32 v101, v101
	v_mul_f32_e32 v102, v14, v96
	v_mul_f32_e32 v103, v30, v96
	v_add_f32_e32 v100, 1.0, v100
	v_add_f32_e32 v101, 1.0, v101
	v_rcp_f32_e32 v100, v100
	v_rcp_f32_e32 v101, v101
	s_nop 0
	v_mul_f32_e32 v58, v100, v58
	v_mul_f32_e32 v59, v101, v59
	v_mul_f32_e32 v58, v102, v58
	v_mul_f32_e32 v59, v103, v59
	v_cvt_pk_bf16_f32 v58, v58, v58
	v_cvt_pk_bf16_f32 v59, v59, v59
	s_waitcnt vmcnt(4)
	v_lshlrev_b32_e32 v60, 16, v60
	v_lshlrev_b32_e32 v61, 16, v61
	v_mul_f32_e32 v100, 0xbfb8aa3b, v60
	v_mul_f32_e32 v101, 0xbfb8aa3b, v61
	v_exp_f32_e32 v100, v100
	v_exp_f32_e32 v101, v101
	v_mul_f32_e32 v102, v15, v97
	v_mul_f32_e32 v103, v31, v97
	v_add_f32_e32 v100, 1.0, v100
	v_add_f32_e32 v101, 1.0, v101
	v_rcp_f32_e32 v100, v100
	v_rcp_f32_e32 v101, v101
	s_nop 0
	v_mul_f32_e32 v60, v100, v60
	v_mul_f32_e32 v61, v101, v61
	v_mul_f32_e32 v60, v102, v60
	v_mul_f32_e32 v61, v103, v61
	v_cvt_pk_bf16_f32 v60, v60, v60
	v_cvt_pk_bf16_f32 v61, v61, v61
	s_waitcnt vmcnt(2)
	v_lshlrev_b32_e32 v62, 16, v62
	v_lshlrev_b32_e32 v63, 16, v63
	v_mul_f32_e32 v100, 0xbfb8aa3b, v62
	v_mul_f32_e32 v101, 0xbfb8aa3b, v63
	v_exp_f32_e32 v100, v100
	v_exp_f32_e32 v101, v101
	v_mul_f32_e32 v102, v16, v98
	v_mul_f32_e32 v103, v32, v98
	v_add_f32_e32 v100, 1.0, v100
	v_add_f32_e32 v101, 1.0, v101
	v_rcp_f32_e32 v100, v100
	v_rcp_f32_e32 v101, v101
	s_nop 0
	v_mul_f32_e32 v62, v100, v62
	v_mul_f32_e32 v63, v101, v63
	v_mul_f32_e32 v62, v102, v62
	v_mul_f32_e32 v63, v103, v63
	v_cvt_pk_bf16_f32 v62, v62, v62
	v_cvt_pk_bf16_f32 v63, v63, v63
	s_waitcnt vmcnt(0)
	v_lshlrev_b32_e32 v64, 16, v64
	v_lshlrev_b32_e32 v65, 16, v65
	v_mul_f32_e32 v100, 0xbfb8aa3b, v64
	v_mul_f32_e32 v101, 0xbfb8aa3b, v65
	v_exp_f32_e32 v100, v100
	v_exp_f32_e32 v101, v101
	v_mul_f32_e32 v102, v17, v99
	v_mul_f32_e32 v103, v33, v99
	v_add_f32_e32 v100, 1.0, v100
	v_add_f32_e32 v101, 1.0, v101
	v_rcp_f32_e32 v100, v100
	v_rcp_f32_e32 v101, v101
	s_nop 0
	v_mul_f32_e32 v64, v100, v64
	v_mul_f32_e32 v65, v101, v65
	v_mul_f32_e32 v64, v102, v64
	v_mul_f32_e32 v65, v103, v65
	v_cvt_pk_bf16_f32 v64, v64, v64
	v_cvt_pk_bf16_f32 v65, v65, v65
	s_mov_b32 s8, s74
	s_mov_b32 s9, s75
	global_store_short v104, v34, s[8:9] offset:0
	global_store_short v104, v35, s[8:9] offset:64
	s_add_u32 s8, s8, 0x2000
	s_addc_u32 s9, s9, 0
	global_store_short v104, v36, s[8:9] offset:0
	global_store_short v104, v37, s[8:9] offset:64
	s_add_u32 s8, s8, 0x2000
	s_addc_u32 s9, s9, 0
	global_store_short v104, v38, s[8:9] offset:0
	global_store_short v104, v39, s[8:9] offset:64
	s_add_u32 s8, s8, 0x2000
	s_addc_u32 s9, s9, 0
	global_store_short v104, v40, s[8:9] offset:0
	global_store_short v104, v41, s[8:9] offset:64
	s_add_u32 s8, s8, 0xa000
	s_addc_u32 s9, s9, 0
	global_store_short v104, v42, s[8:9] offset:0
	global_store_short v104, v43, s[8:9] offset:64
	s_add_u32 s8, s8, 0x2000
	s_addc_u32 s9, s9, 0
	global_store_short v104, v44, s[8:9] offset:0
	global_store_short v104, v45, s[8:9] offset:64
	s_add_u32 s8, s8, 0x2000
	s_addc_u32 s9, s9, 0
	global_store_short v104, v46, s[8:9] offset:0
	global_store_short v104, v47, s[8:9] offset:64
	s_add_u32 s8, s8, 0x2000
	s_addc_u32 s9, s9, 0
	global_store_short v104, v48, s[8:9] offset:0
	global_store_short v104, v49, s[8:9] offset:64
	s_add_u32 s8, s8, 0xa000
	s_addc_u32 s9, s9, 0
	global_store_short v104, v50, s[8:9] offset:0
	global_store_short v104, v51, s[8:9] offset:64
	s_add_u32 s8, s8, 0x2000
	s_addc_u32 s9, s9, 0
	global_store_short v104, v52, s[8:9] offset:0
	global_store_short v104, v53, s[8:9] offset:64
	s_add_u32 s8, s8, 0x2000
	s_addc_u32 s9, s9, 0
	global_store_short v104, v54, s[8:9] offset:0
	global_store_short v104, v55, s[8:9] offset:64
	s_add_u32 s8, s8, 0x2000
	s_addc_u32 s9, s9, 0
	global_store_short v104, v56, s[8:9] offset:0
	global_store_short v104, v57, s[8:9] offset:64
	s_add_u32 s8, s8, 0xa000
	s_addc_u32 s9, s9, 0
	global_store_short v104, v58, s[8:9] offset:0
	global_store_short v104, v59, s[8:9] offset:64
	s_add_u32 s8, s8, 0x2000
	s_addc_u32 s9, s9, 0
	global_store_short v104, v60, s[8:9] offset:0
	global_store_short v104, v61, s[8:9] offset:64
	s_add_u32 s8, s8, 0x2000
	s_addc_u32 s9, s9, 0
	global_store_short v104, v62, s[8:9] offset:0
	global_store_short v104, v63, s[8:9] offset:64
	s_add_u32 s8, s8, 0x2000
	s_addc_u32 s9, s9, 0
	global_store_short v104, v64, s[8:9] offset:0
	global_store_short v104, v65, s[8:9] offset:64
	s_branch .LBB0_193

.LBB0_256:
	s_lshl_b32 s8, s92, 6
	s_lshl_b32 s8, s8, 1
	s_add_u32 s8, s34, s8
	s_addc_u32 s9, s35, 0
	s_add_u32 s74, s8, 0x1800
	s_addc_u32 s75, s9, 0
	s_and_b64 vcc, exec, s[6:7]
	s_cbranch_vccz .LBB0_260
	s_and_saveexec_b64 s[8:9], s[76:77]
	ds_write_b32 v134, v128 offset:32768
	s_or_b64 exec, exec, s[8:9]
	s_waitcnt lgkmcnt(0)
	v_add_u32_e32 v105, v109, v119
	ds_read_b128 v[68:71], v105 offset:32768
	ds_read_b128 v[72:75], v105 offset:32800
	ds_read_b128 v[76:79], v105 offset:32832
	ds_read_b128 v[80:83], v105 offset:32864
	v_lshl_add_u32 v104, v108, 1, v120
	v_add_u32_e32 v104, v104, v122
	s_mov_b32 s8, s74
	s_mov_b32 s9, s75
	global_load_ushort v34, v104, s[8:9] offset:0
	global_load_ushort v35, v104, s[8:9] offset:64
	s_add_u32 s8, s8, 0x2000
	s_addc_u32 s9, s9, 0
	global_load_ushort v36, v104, s[8:9] offset:0
	global_load_ushort v37, v104, s[8:9] offset:64
	s_add_u32 s8, s8, 0x2000
	s_addc_u32 s9, s9, 0
	global_load_ushort v38, v104, s[8:9] offset:0
	global_load_ushort v39, v104, s[8:9] offset:64
	s_add_u32 s8, s8, 0x2000
	s_addc_u32 s9, s9, 0
	global_load_ushort v40, v104, s[8:9] offset:0
	global_load_ushort v41, v104, s[8:9] offset:64
	s_add_u32 s8, s8, 0xa000
	s_addc_u32 s9, s9, 0
	global_load_ushort v42, v104, s[8:9] offset:0
	global_load_ushort v43, v104, s[8:9] offset:64
	s_add_u32 s8, s8, 0x2000
	s_addc_u32 s9, s9, 0
	global_load_ushort v44, v104, s[8:9] offset:0
	global_load_ushort v45, v104, s[8:9] offset:64
	s_add_u32 s8, s8, 0x2000
	s_addc_u32 s9, s9, 0
	global_load_ushort v46, v104, s[8:9] offset:0
	global_load_ushort v47, v104, s[8:9] offset:64
	s_add_u32 s8, s8, 0x2000
	s_addc_u32 s9, s9, 0
	global_load_ushort v48, v104, s[8:9] offset:0
	global_load_ushort v49, v104, s[8:9] offset:64
	s_add_u32 s8, s8, 0xa000
	s_addc_u32 s9, s9, 0
	global_load_ushort v50, v104, s[8:9] offset:0
	global_load_ushort v51, v104, s[8:9] offset:64
	s_add_u32 s8, s8, 0x2000
	s_addc_u32 s9, s9, 0
	global_load_ushort v52, v104, s[8:9] offset:0
	global_load_ushort v53, v104, s[8:9] offset:64
	s_add_u32 s8, s8, 0x2000
	s_addc_u32 s9, s9, 0
	global_load_ushort v54, v104, s[8:9] offset:0
	global_load_ushort v55, v104, s[8:9] offset:64
	s_add_u32 s8, s8, 0x2000
	s_addc_u32 s9, s9, 0
	global_load_ushort v56, v104, s[8:9] offset:0
	global_load_ushort v57, v104, s[8:9] offset:64
	s_add_u32 s8, s8, 0xa000
	s_addc_u32 s9, s9, 0
	global_load_ushort v58, v104, s[8:9] offset:0
	global_load_ushort v59, v104, s[8:9] offset:64
	s_add_u32 s8, s8, 0x2000
	s_addc_u32 s9, s9, 0
	global_load_ushort v60, v104, s[8:9] offset:0
	global_load_ushort v61, v104, s[8:9] offset:64
	s_add_u32 s8, s8, 0x2000
	s_addc_u32 s9, s9, 0
	global_load_ushort v62, v104, s[8:9] offset:0
	global_load_ushort v63, v104, s[8:9] offset:64
	s_add_u32 s8, s8, 0x2000
	s_addc_u32 s9, s9, 0
	global_load_ushort v64, v104, s[8:9] offset:0
	global_load_ushort v65, v104, s[8:9] offset:64
	s_waitcnt lgkmcnt(0)
	v_rcp_f32_e32 v84, v68
	v_rcp_f32_e32 v85, v69
	v_rcp_f32_e32 v86, v70
	v_rcp_f32_e32 v87, v71
	v_rcp_f32_e32 v88, v72
	v_rcp_f32_e32 v89, v73
	v_rcp_f32_e32 v90, v74
	v_rcp_f32_e32 v91, v75
	v_rcp_f32_e32 v92, v76
	v_rcp_f32_e32 v93, v77
	v_rcp_f32_e32 v94, v78
	v_rcp_f32_e32 v95, v79
	v_rcp_f32_e32 v96, v80
	v_rcp_f32_e32 v97, v81
	v_rcp_f32_e32 v98, v82
	v_rcp_f32_e32 v99, v83
	s_waitcnt vmcnt(30)
	v_lshlrev_b32_e32 v34, 16, v34
	v_lshlrev_b32_e32 v35, 16, v35
	v_mul_f32_e32 v100, 0xbfb8aa3b, v34
	v_mul_f32_e32 v101, 0xbfb8aa3b, v35
	v_exp_f32_e32 v100, v100
	v_exp_f32_e32 v101, v101
	v_mul_f32_e32 v102, v2, v84
	v_mul_f32_e32 v103, v18, v84
	v_add_f32_e32 v100, 1.0, v100
	v_add_f32_e32 v101, 1.0, v101
	v_rcp_f32_e32 v100, v100
	v_rcp_f32_e32 v101, v101
	s_nop 0
	v_mul_f32_e32 v34, v100, v34
	v_mul_f32_e32 v35, v101, v35
	v_mul_f32_e32 v34, v102, v34
	v_mul_f32_e32 v35, v103, v35
	v_cvt_pk_bf16_f32 v34, v34, v34
	v_cvt_pk_bf16_f32 v35, v35, v35
	s_waitcnt vmcnt(28)
	v_lshlrev_b32_e32 v36, 16, v36
	v_lshlrev_b32_e32 v37, 16, v37
	v_mul_f32_e32 v100, 0xbfb8aa3b, v36
	v_mul_f32_e32 v101, 0xbfb8aa3b, v37
	v_exp_f32_e32 v100, v100
	v_exp_f32_e32 v101, v101
	v_mul_f32_e32 v102, v3, v85
	v_mul_f32_e32 v103, v19, v85
	v_add_f32_e32 v100, 1.0, v100
	v_add_f32_e32 v101, 1.0, v101
	v_rcp_f32_e32 v100, v100
	v_rcp_f32_e32 v101, v101
	s_nop 0
	v_mul_f32_e32 v36, v100, v36
	v_mul_f32_e32 v37, v101, v37
	v_mul_f32_e32 v36, v102, v36
	v_mul_f32_e32 v37, v103, v37
	v_cvt_pk_bf16_f32 v36, v36, v36
	v_cvt_pk_bf16_f32 v37, v37, v37
	s_waitcnt vmcnt(26)
	v_lshlrev_b32_e32 v38, 16, v38
	v_lshlrev_b32_e32 v39, 16, v39
	v_mul_f32_e32 v100, 0xbfb8aa3b, v38
	v_mul_f32_e32 v101, 0xbfb8aa3b, v39
	v_exp_f32_e32 v100, v100
	v_exp_f32_e32 v101, v101
	v_mul_f32_e32 v102, v4, v86
	v_mul_f32_e32 v103, v20, v86
	v_add_f32_e32 v100, 1.0, v100
	v_add_f32_e32 v101, 1.0, v101
	v_rcp_f32_e32 v100, v100
	v_rcp_f32_e32 v101, v101
	s_nop 0
	v_mul_f32_e32 v38, v100, v38
	v_mul_f32_e32 v39, v101, v39
	v_mul_f32_e32 v38, v102, v38
	v_mul_f32_e32 v39, v103, v39
	v_cvt_pk_bf16_f32 v38, v38, v38
	v_cvt_pk_bf16_f32 v39, v39, v39
	s_waitcnt vmcnt(24)
	v_lshlrev_b32_e32 v40, 16, v40
	v_lshlrev_b32_e32 v41, 16, v41
	v_mul_f32_e32 v100, 0xbfb8aa3b, v40
	v_mul_f32_e32 v101, 0xbfb8aa3b, v41
	v_exp_f32_e32 v100, v100
	v_exp_f32_e32 v101, v101
	v_mul_f32_e32 v102, v5, v87
	v_mul_f32_e32 v103, v21, v87
	v_add_f32_e32 v100, 1.0, v100
	v_add_f32_e32 v101, 1.0, v101
	v_rcp_f32_e32 v100, v100
	v_rcp_f32_e32 v101, v101
	s_nop 0
	v_mul_f32_e32 v40, v100, v40
	v_mul_f32_e32 v41, v101, v41
	v_mul_f32_e32 v40, v102, v40
	v_mul_f32_e32 v41, v103, v41
	v_cvt_pk_bf16_f32 v40, v40, v40
	v_cvt_pk_bf16_f32 v41, v41, v41
	s_waitcnt vmcnt(22)
	v_lshlrev_b32_e32 v42, 16, v42
	v_lshlrev_b32_e32 v43, 16, v43
	v_mul_f32_e32 v100, 0xbfb8aa3b, v42
	v_mul_f32_e32 v101, 0xbfb8aa3b, v43
	v_exp_f32_e32 v100, v100
	v_exp_f32_e32 v101, v101
	v_mul_f32_e32 v102, v6, v88
	v_mul_f32_e32 v103, v22, v88
	v_add_f32_e32 v100, 1.0, v100
	v_add_f32_e32 v101, 1.0, v101
	v_rcp_f32_e32 v100, v100
	v_rcp_f32_e32 v101, v101
	s_nop 0
	v_mul_f32_e32 v42, v100, v42
	v_mul_f32_e32 v43, v101, v43
	v_mul_f32_e32 v42, v102, v42
	v_mul_f32_e32 v43, v103, v43
	v_cvt_pk_bf16_f32 v42, v42, v42
	v_cvt_pk_bf16_f32 v43, v43, v43
	s_waitcnt vmcnt(20)
	v_lshlrev_b32_e32 v44, 16, v44
	v_lshlrev_b32_e32 v45, 16, v45
	v_mul_f32_e32 v100, 0xbfb8aa3b, v44
	v_mul_f32_e32 v101, 0xbfb8aa3b, v45
	v_exp_f32_e32 v100, v100
	v_exp_f32_e32 v101, v101
	v_mul_f32_e32 v102, v7, v89
	v_mul_f32_e32 v103, v23, v89
	v_add_f32_e32 v100, 1.0, v100
	v_add_f32_e32 v101, 1.0, v101
	v_rcp_f32_e32 v100, v100
	v_rcp_f32_e32 v101, v101
	s_nop 0
	v_mul_f32_e32 v44, v100, v44
	v_mul_f32_e32 v45, v101, v45
	v_mul_f32_e32 v44, v102, v44
	v_mul_f32_e32 v45, v103, v45
	v_cvt_pk_bf16_f32 v44, v44, v44
	v_cvt_pk_bf16_f32 v45, v45, v45
	s_waitcnt vmcnt(18)
	v_lshlrev_b32_e32 v46, 16, v46
	v_lshlrev_b32_e32 v47, 16, v47
	v_mul_f32_e32 v100, 0xbfb8aa3b, v46
	v_mul_f32_e32 v101, 0xbfb8aa3b, v47
	v_exp_f32_e32 v100, v100
	v_exp_f32_e32 v101, v101
	v_mul_f32_e32 v102, v8, v90
	v_mul_f32_e32 v103, v24, v90
	v_add_f32_e32 v100, 1.0, v100
	v_add_f32_e32 v101, 1.0, v101
	v_rcp_f32_e32 v100, v100
	v_rcp_f32_e32 v101, v101
	s_nop 0
	v_mul_f32_e32 v46, v100, v46
	v_mul_f32_e32 v47, v101, v47
	v_mul_f32_e32 v46, v102, v46
	v_mul_f32_e32 v47, v103, v47
	v_cvt_pk_bf16_f32 v46, v46, v46
	v_cvt_pk_bf16_f32 v47, v47, v47
	s_waitcnt vmcnt(16)
	v_lshlrev_b32_e32 v48, 16, v48
	v_lshlrev_b32_e32 v49, 16, v49
	v_mul_f32_e32 v100, 0xbfb8aa3b, v48
	v_mul_f32_e32 v101, 0xbfb8aa3b, v49
	v_exp_f32_e32 v100, v100
	v_exp_f32_e32 v101, v101
	v_mul_f32_e32 v102, v9, v91
	v_mul_f32_e32 v103, v25, v91
	v_add_f32_e32 v100, 1.0, v100
	v_add_f32_e32 v101, 1.0, v101
	v_rcp_f32_e32 v100, v100
	v_rcp_f32_e32 v101, v101
	s_nop 0
	v_mul_f32_e32 v48, v100, v48
	v_mul_f32_e32 v49, v101, v49
	v_mul_f32_e32 v48, v102, v48
	v_mul_f32_e32 v49, v103, v49
	v_cvt_pk_bf16_f32 v48, v48, v48
	v_cvt_pk_bf16_f32 v49, v49, v49
	s_waitcnt vmcnt(14)
	v_lshlrev_b32_e32 v50, 16, v50
	v_lshlrev_b32_e32 v51, 16, v51
	v_mul_f32_e32 v100, 0xbfb8aa3b, v50
	v_mul_f32_e32 v101, 0xbfb8aa3b, v51
	v_exp_f32_e32 v100, v100
	v_exp_f32_e32 v101, v101
	v_mul_f32_e32 v102, v10, v92
	v_mul_f32_e32 v103, v26, v92
	v_add_f32_e32 v100, 1.0, v100
	v_add_f32_e32 v101, 1.0, v101
	v_rcp_f32_e32 v100, v100
	v_rcp_f32_e32 v101, v101
	s_nop 0
	v_mul_f32_e32 v50, v100, v50
	v_mul_f32_e32 v51, v101, v51
	v_mul_f32_e32 v50, v102, v50
	v_mul_f32_e32 v51, v103, v51
	v_cvt_pk_bf16_f32 v50, v50, v50
	v_cvt_pk_bf16_f32 v51, v51, v51
	s_waitcnt vmcnt(12)
	v_lshlrev_b32_e32 v52, 16, v52
	v_lshlrev_b32_e32 v53, 16, v53
	v_mul_f32_e32 v100, 0xbfb8aa3b, v52
	v_mul_f32_e32 v101, 0xbfb8aa3b, v53
	v_exp_f32_e32 v100, v100
	v_exp_f32_e32 v101, v101
	v_mul_f32_e32 v102, v11, v93
	v_mul_f32_e32 v103, v27, v93
	v_add_f32_e32 v100, 1.0, v100
	v_add_f32_e32 v101, 1.0, v101
	v_rcp_f32_e32 v100, v100
	v_rcp_f32_e32 v101, v101
	s_nop 0
	v_mul_f32_e32 v52, v100, v52
	v_mul_f32_e32 v53, v101, v53
	v_mul_f32_e32 v52, v102, v52
	v_mul_f32_e32 v53, v103, v53
	v_cvt_pk_bf16_f32 v52, v52, v52
	v_cvt_pk_bf16_f32 v53, v53, v53
	s_waitcnt vmcnt(10)
	v_lshlrev_b32_e32 v54, 16, v54
	v_lshlrev_b32_e32 v55, 16, v55
	v_mul_f32_e32 v100, 0xbfb8aa3b, v54
	v_mul_f32_e32 v101, 0xbfb8aa3b, v55
	v_exp_f32_e32 v100, v100
	v_exp_f32_e32 v101, v101
	v_mul_f32_e32 v102, v12, v94
	v_mul_f32_e32 v103, v28, v94
	v_add_f32_e32 v100, 1.0, v100
	v_add_f32_e32 v101, 1.0, v101
	v_rcp_f32_e32 v100, v100
	v_rcp_f32_e32 v101, v101
	s_nop 0
	v_mul_f32_e32 v54, v100, v54
	v_mul_f32_e32 v55, v101, v55
	v_mul_f32_e32 v54, v102, v54
	v_mul_f32_e32 v55, v103, v55
	v_cvt_pk_bf16_f32 v54, v54, v54
	v_cvt_pk_bf16_f32 v55, v55, v55
	s_waitcnt vmcnt(8)
	v_lshlrev_b32_e32 v56, 16, v56
	v_lshlrev_b32_e32 v57, 16, v57
	v_mul_f32_e32 v100, 0xbfb8aa3b, v56
	v_mul_f32_e32 v101, 0xbfb8aa3b, v57
	v_exp_f32_e32 v100, v100
	v_exp_f32_e32 v101, v101
	v_mul_f32_e32 v102, v13, v95
	v_mul_f32_e32 v103, v29, v95
	v_add_f32_e32 v100, 1.0, v100
	v_add_f32_e32 v101, 1.0, v101
	v_rcp_f32_e32 v100, v100
	v_rcp_f32_e32 v101, v101
	s_nop 0
	v_mul_f32_e32 v56, v100, v56
	v_mul_f32_e32 v57, v101, v57
	v_mul_f32_e32 v56, v102, v56
	v_mul_f32_e32 v57, v103, v57
	v_cvt_pk_bf16_f32 v56, v56, v56
	v_cvt_pk_bf16_f32 v57, v57, v57
	s_waitcnt vmcnt(6)
	v_lshlrev_b32_e32 v58, 16, v58
	v_lshlrev_b32_e32 v59, 16, v59
	v_mul_f32_e32 v100, 0xbfb8aa3b, v58
	v_mul_f32_e32 v101, 0xbfb8aa3b, v59
	v_exp_f32_e32 v100, v100
	v_exp_f32_e32 v101, v101
	v_mul_f32_e32 v102, v14, v96
	v_mul_f32_e32 v103, v30, v96
	v_add_f32_e32 v100, 1.0, v100
	v_add_f32_e32 v101, 1.0, v101
	v_rcp_f32_e32 v100, v100
	v_rcp_f32_e32 v101, v101
	s_nop 0
	v_mul_f32_e32 v58, v100, v58
	v_mul_f32_e32 v59, v101, v59
	v_mul_f32_e32 v58, v102, v58
	v_mul_f32_e32 v59, v103, v59
	v_cvt_pk_bf16_f32 v58, v58, v58
	v_cvt_pk_bf16_f32 v59, v59, v59
	s_waitcnt vmcnt(4)
	v_lshlrev_b32_e32 v60, 16, v60
	v_lshlrev_b32_e32 v61, 16, v61
	v_mul_f32_e32 v100, 0xbfb8aa3b, v60
	v_mul_f32_e32 v101, 0xbfb8aa3b, v61
	v_exp_f32_e32 v100, v100
	v_exp_f32_e32 v101, v101
	v_mul_f32_e32 v102, v15, v97
	v_mul_f32_e32 v103, v31, v97
	v_add_f32_e32 v100, 1.0, v100
	v_add_f32_e32 v101, 1.0, v101
	v_rcp_f32_e32 v100, v100
	v_rcp_f32_e32 v101, v101
	s_nop 0
	v_mul_f32_e32 v60, v100, v60
	v_mul_f32_e32 v61, v101, v61
	v_mul_f32_e32 v60, v102, v60
	v_mul_f32_e32 v61, v103, v61
	v_cvt_pk_bf16_f32 v60, v60, v60
	v_cvt_pk_bf16_f32 v61, v61, v61
	s_waitcnt vmcnt(2)
	v_lshlrev_b32_e32 v62, 16, v62
	v_lshlrev_b32_e32 v63, 16, v63
	v_mul_f32_e32 v100, 0xbfb8aa3b, v62
	v_mul_f32_e32 v101, 0xbfb8aa3b, v63
	v_exp_f32_e32 v100, v100
	v_exp_f32_e32 v101, v101
	v_mul_f32_e32 v102, v16, v98
	v_mul_f32_e32 v103, v32, v98
	v_add_f32_e32 v100, 1.0, v100
	v_add_f32_e32 v101, 1.0, v101
	v_rcp_f32_e32 v100, v100
	v_rcp_f32_e32 v101, v101
	s_nop 0
	v_mul_f32_e32 v62, v100, v62
	v_mul_f32_e32 v63, v101, v63
	v_mul_f32_e32 v62, v102, v62
	v_mul_f32_e32 v63, v103, v63
	v_cvt_pk_bf16_f32 v62, v62, v62
	v_cvt_pk_bf16_f32 v63, v63, v63
	s_waitcnt vmcnt(0)
	v_lshlrev_b32_e32 v64, 16, v64
	v_lshlrev_b32_e32 v65, 16, v65
	v_mul_f32_e32 v100, 0xbfb8aa3b, v64
	v_mul_f32_e32 v101, 0xbfb8aa3b, v65
	v_exp_f32_e32 v100, v100
	v_exp_f32_e32 v101, v101
	v_mul_f32_e32 v102, v17, v99
	v_mul_f32_e32 v103, v33, v99
	v_add_f32_e32 v100, 1.0, v100
	v_add_f32_e32 v101, 1.0, v101
	v_rcp_f32_e32 v100, v100
	v_rcp_f32_e32 v101, v101
	s_nop 0
	v_mul_f32_e32 v64, v100, v64
	v_mul_f32_e32 v65, v101, v65
	v_mul_f32_e32 v64, v102, v64
	v_mul_f32_e32 v65, v103, v65
	v_cvt_pk_bf16_f32 v64, v64, v64
	v_cvt_pk_bf16_f32 v65, v65, v65
	s_mov_b32 s8, s74
	s_mov_b32 s9, s75
	global_store_short v104, v34, s[8:9] offset:0
	global_store_short v104, v35, s[8:9] offset:64
	s_add_u32 s8, s8, 0x2000
	s_addc_u32 s9, s9, 0
	global_store_short v104, v36, s[8:9] offset:0
	global_store_short v104, v37, s[8:9] offset:64
	s_add_u32 s8, s8, 0x2000
	s_addc_u32 s9, s9, 0
	global_store_short v104, v38, s[8:9] offset:0
	global_store_short v104, v39, s[8:9] offset:64
	s_add_u32 s8, s8, 0x2000
	s_addc_u32 s9, s9, 0
	global_store_short v104, v40, s[8:9] offset:0
	global_store_short v104, v41, s[8:9] offset:64
	s_add_u32 s8, s8, 0xa000
	s_addc_u32 s9, s9, 0
	global_store_short v104, v42, s[8:9] offset:0
	global_store_short v104, v43, s[8:9] offset:64
	s_add_u32 s8, s8, 0x2000
	s_addc_u32 s9, s9, 0
	global_store_short v104, v44, s[8:9] offset:0
	global_store_short v104, v45, s[8:9] offset:64
	s_add_u32 s8, s8, 0x2000
	s_addc_u32 s9, s9, 0
	global_store_short v104, v46, s[8:9] offset:0
	global_store_short v104, v47, s[8:9] offset:64
	s_add_u32 s8, s8, 0x2000
	s_addc_u32 s9, s9, 0
	global_store_short v104, v48, s[8:9] offset:0
	global_store_short v104, v49, s[8:9] offset:64
	s_add_u32 s8, s8, 0xa000
	s_addc_u32 s9, s9, 0
	global_store_short v104, v50, s[8:9] offset:0
	global_store_short v104, v51, s[8:9] offset:64
	s_add_u32 s8, s8, 0x2000
	s_addc_u32 s9, s9, 0
	global_store_short v104, v52, s[8:9] offset:0
	global_store_short v104, v53, s[8:9] offset:64
	s_add_u32 s8, s8, 0x2000
	s_addc_u32 s9, s9, 0
	global_store_short v104, v54, s[8:9] offset:0
	global_store_short v104, v55, s[8:9] offset:64
	s_add_u32 s8, s8, 0x2000
	s_addc_u32 s9, s9, 0
	global_store_short v104, v56, s[8:9] offset:0
	global_store_short v104, v57, s[8:9] offset:64
	s_add_u32 s8, s8, 0xa000
	s_addc_u32 s9, s9, 0
	global_store_short v104, v58, s[8:9] offset:0
	global_store_short v104, v59, s[8:9] offset:64
	s_add_u32 s8, s8, 0x2000
	s_addc_u32 s9, s9, 0
	global_store_short v104, v60, s[8:9] offset:0
	global_store_short v104, v61, s[8:9] offset:64
	s_add_u32 s8, s8, 0x2000
	s_addc_u32 s9, s9, 0
	global_store_short v104, v62, s[8:9] offset:0
	global_store_short v104, v63, s[8:9] offset:64
	s_add_u32 s8, s8, 0x2000
	s_addc_u32 s9, s9, 0
	global_store_short v104, v64, s[8:9] offset:0
	global_store_short v104, v65, s[8:9] offset:64
	s_branch .LBB0_164

.LBB0_269:
	s_and_b64 vcc, exec, s[6:7]
	s_cbranch_vccz .LBB0_532
	s_cmp_gt_i32 s80, 3
	s_mov_b64 s[6:7], -1
	s_cbranch_scc0 .LBB0_529
	s_cmp_lt_i32 s80, 5
	s_mov_b64 s[4:5], -1
	s_cbranch_scc1 .LBB0_507
	s_cmp_gt_i32 s80, 5
	s_cbranch_scc0 .LBB0_309
	s_cmp_eq_u32 s81, 0
	s_movk_i32 s2, 0x400
	s_cselect_b32 s2, s2, 0x420
	s_cmp_ge_i32 s72, s2
	s_cbranch_scc1 .LBB0_308
	s_load_dwordx2 s[4:5], s[0:1], 0x48
	s_add_u32 s16, s98, 0x4600000
	s_addc_u32 s17, s99, 0
	s_lshl_b32 s6, s83, 7
	s_ashr_i32 s7, s6, 31
	s_lshl_b64 s[6:7], s[6:7], 2
	s_waitcnt lgkmcnt(0)
	s_add_u32 s4, s4, s6
	s_addc_u32 s5, s5, s7
	s_add_u32 s18, s98, 0x4600800
	s_addc_u32 s19, s99, 0
	s_add_u32 s20, s98, 0x4600a00
	s_addc_u32 s21, s99, 0
	v_and_b32_e32 v0, 0x3fffffc0, v178
	s_add_i32 s6, 16, 0x10000
	v_lshl_add_u32 v220, v0, 2, s6
	v_ashrrev_i32_e32 v0, 1, v178
	s_movk_i32 s6, 0xffe0
	v_and_b32_e32 v7, 0xffffffe0, v0
	v_bfi_b32 v221, s6, v0, v178
	v_and_b32_e32 v0, 32, v178
	v_lshl_add_u64 v[182:183], s[4:5], 0, v[0:1]
	v_ashrrev_i32_e32 v184, 4, v178
	v_lshlrev_b32_e32 v0, 3, v178
	v_lshlrev_b32_e32 v13, 5, v184
	v_and_b32_e32 v14, 24, v0
	s_movk_i32 s5, 0xe0
	v_lshrrev_b32_e32 v11, 5, v178
	v_bfe_u32 v12, v0, 5, 2
	s_mov_b32 s4, 0x7ffffc
	v_and_or_b32 v13, v13, s5, v14
	v_and_or_b32 v11, v11, s4, v12
	v_lshlrev_b32_e32 v13, 1, v13
	v_lshl_or_b32 v222, v11, 9, v13
	v_add_u32_e32 v11, 32, v184
	v_lshrrev_b32_e32 v14, 1, v11
	v_bfe_u32 v5, v178, 5, 1
	v_and_b32_e32 v6, 0x78, v0
	v_and_or_b32 v12, v14, s4, v12
	v_lshlrev_b32_e32 v8, 4, v178
	v_lshl_or_b32 v223, v12, 9, v13
	v_lshlrev_b32_e32 v13, 1, v6
	v_and_b32_e32 v14, 0xf0, v178
	v_lshlrev_b32_e32 v11, 8, v11
	v_lshlrev_b32_e32 v226, 4, v5
	s_movk_i32 s4, 0xf0
	v_bitop3_b32 v225, v13, v11, v14 bitop3:0xde
	v_and_b32_e32 v11, 0xf0, v8
	v_bitop3_b32 v228, v226, v8, s4 bitop3:0x78
	s_movk_i32 s4, 0x60
	v_bitop3_b32 v231, v226, v11, s4 bitop3:0x36
	s_movk_i32 s4, 0x80
	v_bitop3_b32 v232, v226, v11, s4 bitop3:0x36
	s_movk_i32 s4, 0xa0
	v_lshlrev_b32_e32 v10, 1, v178
	v_bitop3_b32 v233, v226, v11, s4 bitop3:0x36
	s_movk_i32 s4, 0xc0
	v_mad_i64_i32 v[180:181], s[6:7], v221, s65, 0
	v_and_b32_e32 v10, 32, v10
	v_bitop3_b32 v234, v226, v11, s4 bitop3:0x36
	s_movk_i32 s4, 0x118
	s_cmp_lg_u32 16, -1
	v_and_b32_e32 v9, 0xc0, v8
	v_and_or_b32 v0, v0, s4, v10
	s_cselect_b32 s6, 16, 0
	v_add3_u32 v237, v9, s6, v0
	s_lshl_b64 s[6:7], 1, s47
	s_and_b32 s92, s6, 0xfff72ef6
	v_mad_i64_i32 v[188:189], s[8:9], v7, s65, 0
	v_lshlrev_b32_e32 v0, 6, v5
	v_and_b32_e32 v2, 31, v178
	v_and_b32_e32 v3, 63, v178
	v_lshlrev_b32_e32 v4, 3, v5
	v_ashrrev_i32_e32 v185, 31, v184
	v_lshlrev_b32_e32 v12, 8, v184
	s_cmp_lg_u64 s[92:93], 0
	v_lshl_add_u64 v[8:9], s[98:99], 0, v[0:1]
	s_mov_b64 s[8:9], 0x1d57c000
	v_lshl_add_u64 v[186:187], v[184:185], 0, 32
	v_bitop3_b32 v224, v13, v12, v14 bitop3:0xde
	v_lshl_add_u32 v227, v2, 8, 16
	v_bitop3_b32 v229, v226, v11, 32 bitop3:0x36
	v_bitop3_b32 v230, v226, v11, 64 bitop3:0x36
	v_bitop3_b32 v235, v226, v11, s5 bitop3:0x36
	v_cmp_gt_u32_e64 s[4:5], 32, v3
	v_lshl_add_u32 v236, v2, 2, v220
	s_cselect_b64 s[6:7], -1, 0
	v_ashrrev_i32_e32 v179, 31, v178
	v_mul_u32_u24_e32 v190, 0x5000, v5
	v_mov_b32_e32 v191, v1
	v_lshl_add_u64 v[192:193], v[8:9], 0, s[8:9]
	v_lshlrev_b32_e32 v0, 1, v4
	v_lshlrev_b32_e32 v194, 1, v6
	v_lshlrev_b32_e32 v196, 1, v2
	s_mov_b32 s22, s72
	v_and_b32_e32 v2, 63, v178
	v_lshrrev_b32_e32 v3, 6, v178
	v_lshlrev_b32_e32 v3, 3, v3
	v_lshrrev_b32_e32 v4, 4, v2
	v_add_u32_e32 v4, v3, v4
	v_and_b32_e32 v5, 15, v2
	v_and_b32_e32 v6, 15, v4
	v_xor_b32_e32 v6, v5, v6
	v_lshlrev_b32_e32 v6, 4, v6
	v_mad_u32_u24 v252, v4, s65, v6
	v_add_u32_e32 v4, 4, v4
	v_and_b32_e32 v6, 15, v4
	v_xor_b32_e32 v6, v5, v6
	v_lshlrev_b32_e32 v6, 4, v6
	v_mad_u32_u24 v253, v4, s65, v6
	v_and_b32_e32 v4, 31, v2
	v_lshrrev_b32_e32 v4, 2, v4
	v_add_u32_e32 v4, v3, v4
	v_lshrrev_b32_e32 v5, 5, v2
	v_lshlrev_b32_e32 v5, 6, v5
	v_and_b32_e32 v6, 3, v2
	v_lshlrev_b32_e32 v6, 4, v6
	v_add_u32_e32 v5, v5, v6
	v_add_u32_e32 v5, 0x200, v5
	v_mad_u32_u24 v250, v4, s65, v5
	v_add_u32_e32 v251, 0x80, v250
	s_branch .LBB0_277

.LBB0_285:
	s_lshl_b32 s11, s11, 6
	s_and_b32 s11, s11, 0x100
	s_add_u32 s12, s18, s11
	s_addc_u32 s13, s19, 0
	s_add_u32 s14, s20, s11
	s_addc_u32 s15, s21, 0
	s_ashr_i32 s11, s10, 31
	v_cvt_pk_bf16_f32 v134, v70, v71
	v_cvt_pk_bf16_f32 v135, v72, v73
	v_cvt_pk_bf16_f32 v136, v66, v67
	v_cvt_pk_bf16_f32 v137, v68, v69
	v_cvt_pk_bf16_f32 v142, v62, v63
	v_cvt_pk_bf16_f32 v143, v64, v65
	v_cvt_pk_bf16_f32 v144, v58, v59
	v_cvt_pk_bf16_f32 v145, v60, v61
	v_cvt_pk_bf16_f32 v146, v54, v55
	v_cvt_pk_bf16_f32 v147, v56, v57
	v_cvt_pk_bf16_f32 v148, v50, v51
	v_cvt_pk_bf16_f32 v149, v52, v53
	v_cvt_pk_bf16_f32 v150, v46, v47
	v_cvt_pk_bf16_f32 v151, v48, v49
	v_cvt_pk_bf16_f32 v152, v42, v43
	v_cvt_pk_bf16_f32 v153, v44, v45
	v_cvt_pk_bf16_f32 v154, v38, v39
	v_cvt_pk_bf16_f32 v155, v40, v41
	v_cvt_pk_bf16_f32 v156, v34, v35
	v_cvt_pk_bf16_f32 v157, v32, v33
	v_cvt_pk_bf16_f32 v158, v30, v31
	v_cvt_pk_bf16_f32 v159, v36, v37
	v_cvt_pk_bf16_f32 v160, v78, v81
	v_cvt_pk_bf16_f32 v161, v74, v77
	v_cvt_pk_bf16_f32 v138, v26, v27
	v_cvt_pk_bf16_f32 v139, v28, v29
	v_cvt_pk_bf16_f32 v140, v22, v23
	v_cvt_pk_bf16_f32 v141, v24, v25
	v_cvt_pk_bf16_f32 v130, v18, v19
	v_cvt_pk_bf16_f32 v131, v20, v21
	v_cvt_pk_bf16_f32 v132, v6, v7
	v_cvt_pk_bf16_f32 v133, v2, v3
	v_lshl_add_u64 v[2:3], s[10:11], 0, v[184:185]
	v_mov_b64_e32 v[4:5], s[12:13]
	v_mad_u64_u32 v[6:7], s[24:25], v2, s65, v[4:5]
	v_mad_i32_i24 v7, v3, s65, v7
	v_mov_b32_e32 v195, v1
	v_lshl_add_u64 v[10:11], v[6:7], 0, v[194:195]
	v_lshl_add_u64 v[6:7], v[186:187], 0, s[10:11]
	v_mad_u64_u32 v[4:5], s[24:25], v6, s65, v[4:5]
	v_mad_i32_i24 v5, v7, s65, v5
	v_lshl_add_u64 v[14:15], v[4:5], 0, v[194:195]
	v_mov_b64_e32 v[4:5], s[14:15]
	v_mad_u64_u32 v[8:9], s[24:25], v2, s65, v[4:5]
	v_mad_u64_u32 v[4:5], s[24:25], v6, s65, v[4:5]
	v_mad_i32_i24 v9, v3, s65, v9
	v_mad_i32_i24 v5, v7, s65, v5
	v_lshl_add_u64 v[2:3], v[8:9], 0, v[194:195]
	v_lshl_add_u64 v[6:7], v[4:5], 0, v[194:195]
	global_load_dwordx4 v[2:5], v[2:3], off
	s_nop 0
	global_load_dwordx4 v[6:9], v[6:7], off
	s_nop 0
	global_load_dwordx4 v[10:13], v[10:11], off
	s_nop 0
	global_load_dwordx4 v[14:17], v[14:15], off
	v_lshl_add_u64 v[198:199], s[12:13], 0, v[194:195]
	s_or_b32 s12, s10, 64
	s_ashr_i32 s13, s12, 31
	v_add_u32_e32 v62, 16, v222
	v_lshl_add_u64 v[200:201], s[14:15], 0, v[194:195]
	v_lshl_add_u64 v[18:19], s[12:13], 0, v[184:185]
	v_add_u32_e32 v63, 16, v223
	v_add_u32_e32 v64, 16, v224
	v_add_u32_e32 v67, 16, v225
	v_lshl_add_u64 v[20:21], v[186:187], 0, s[12:13]
	v_mad_u64_u32 v[22:23], s[12:13], v18, s65, v[198:199]
	s_waitcnt vmcnt(0)
	v_mad_u64_u32 v[24:25], s[12:13], v20, s65, v[198:199]
	v_mad_i32_i24 v23, v19, s65, v23
	v_mad_i32_i24 v25, v21, s65, v25
	s_waitcnt vmcnt(3)
	ds_write_b128 v62, v[2:5]
	s_waitcnt vmcnt(2)
	ds_write_b128 v63, v[6:9]
	s_waitcnt vmcnt(1)
	ds_write_b128 v64, v[10:13] offset:32768
	s_waitcnt vmcnt(0)
	ds_write_b128 v67, v[14:17] offset:32768
	v_mad_u64_u32 v[2:3], s[12:13], v18, s65, v[200:201]
	v_mad_i32_i24 v3, v19, s65, v3
	v_mad_u64_u32 v[4:5], s[12:13], v20, s65, v[200:201]
	s_waitcnt lgkmcnt(0)
	s_barrier
	global_load_dwordx4 v[50:53], v[22:23], off
	global_load_dwordx4 v[68:71], v[24:25], off
	v_mad_i32_i24 v5, v21, s65, v5
	global_load_dwordx4 v[54:57], v[2:3], off
	global_load_dwordx4 v[58:61], v[4:5], off
	v_add_u32_e32 v6, v227, v228
	ds_read_b128 v[2:5], v6 offset:32768
	ds_read_b128 v[18:21], v6 offset:40960
	v_add_u32_e32 v38, v227, v229
	ds_read_b128 v[34:37], v38 offset:32768
	ds_read_b128 v[38:41], v38 offset:40960
	s_waitcnt lgkmcnt(3)
	v_mfma_f32_32x32x16_bf16 v[2:17], v[2:5], v[134:137], 0
	s_waitcnt lgkmcnt(2)
	v_mfma_f32_32x32x16_bf16 v[18:33], v[18:21], v[134:137], 0
	s_waitcnt lgkmcnt(1)
	v_mfma_f32_32x32x16_bf16 v[2:17], v[34:37], v[142:145], v[2:17]
	s_waitcnt lgkmcnt(0)
	v_mfma_f32_32x32x16_bf16 v[18:33], v[38:41], v[142:145], v[18:33]
	v_add_u32_e32 v38, v227, v230
	ds_read_b128 v[34:37], v38 offset:32768
	ds_read_b128 v[38:41], v38 offset:40960
	s_waitcnt lgkmcnt(1)
	v_mfma_f32_32x32x16_bf16 v[2:17], v[34:37], v[146:149], v[2:17]
	s_waitcnt lgkmcnt(0)
	v_mfma_f32_32x32x16_bf16 v[18:33], v[38:41], v[146:149], v[18:33]
	v_add_u32_e32 v38, v227, v231
	ds_read_b128 v[34:37], v38 offset:32768
	ds_read_b128 v[38:41], v38 offset:40960
	s_waitcnt lgkmcnt(1)
	v_mfma_f32_32x32x16_bf16 v[2:17], v[34:37], v[150:153], v[2:17]
	s_waitcnt lgkmcnt(0)
	v_mfma_f32_32x32x16_bf16 v[18:33], v[38:41], v[150:153], v[18:33]
	v_add_u32_e32 v38, v227, v232
	ds_read_b128 v[34:37], v38 offset:32768
	ds_read_b128 v[38:41], v38 offset:40960
	s_waitcnt lgkmcnt(1)
	v_mfma_f32_32x32x16_bf16 v[2:17], v[34:37], v[154:157], v[2:17]
	s_waitcnt lgkmcnt(0)
	v_mfma_f32_32x32x16_bf16 v[18:33], v[38:41], v[154:157], v[18:33]
	v_add_u32_e32 v38, v227, v233
	ds_read_b128 v[34:37], v38 offset:32768
	ds_read_b128 v[38:41], v38 offset:40960
	s_waitcnt lgkmcnt(1)
	v_mfma_f32_32x32x16_bf16 v[2:17], v[34:37], v[158:161], v[2:17]
	s_waitcnt lgkmcnt(0)
	v_mfma_f32_32x32x16_bf16 v[18:33], v[38:41], v[158:161], v[18:33]
	v_add_u32_e32 v38, v227, v234
	ds_read_b128 v[34:37], v38 offset:32768
	ds_read_b128 v[38:41], v38 offset:40960
	s_waitcnt lgkmcnt(1)
	v_mfma_f32_32x32x16_bf16 v[2:17], v[34:37], v[138:141], v[2:17]
	s_waitcnt lgkmcnt(0)
	v_mfma_f32_32x32x16_bf16 v[18:33], v[38:41], v[138:141], v[18:33]
	v_add_u32_e32 v38, v227, v235
	ds_read_b128 v[34:37], v38 offset:32768
	ds_read_b128 v[38:41], v38 offset:40960
	s_waitcnt lgkmcnt(1)
	v_mfma_f32_32x32x16_bf16 v[2:17], v[34:37], v[130:133], v[2:17]
	s_waitcnt lgkmcnt(0)
	v_mfma_f32_32x32x16_bf16 v[18:33], v[38:41], v[130:133], v[18:33]
	s_nop 9
	v_max_f32_e32 v34, v3, v3
	v_max_f32_e32 v35, v2, v2
	v_max_f32_e32 v34, v35, v34
	v_max3_f32 v34, v34, v4, v5
	v_max3_f32 v34, v34, v6, v7
	v_max3_f32 v34, v34, v8, v9
	v_max3_f32 v34, v34, v10, v11
	v_max3_f32 v34, v34, v12, v13
	v_max3_f32 v34, v34, v14, v15
	v_max3_f32 v34, v34, v16, v17
	v_max3_f32 v34, v34, v18, v19
	v_max3_f32 v34, v34, v20, v21
	v_max3_f32 v34, v34, v22, v23
	v_max3_f32 v34, v34, v24, v25
	v_max3_f32 v34, v34, v26, v27
	v_max3_f32 v34, v34, v28, v29
	v_max3_f32 v34, v34, v30, v31
	v_max3_f32 v34, v34, v32, v33
	v_mov_b32_e32 v35, v34
	s_nop 1
	v_permlane32_swap_b32_e32 v34, v35
	v_max_f32_e32 v35, v35, v35
	v_max_f32_e32 v34, v34, v34
	v_max_f32_e32 v35, v34, v35
	v_sub_f32_e32 v2, v2, v35
	v_sub_f32_e32 v3, v3, v35
	v_exp_f32_e32 v2, v2
	v_sub_f32_e32 v4, v4, v35
	v_exp_f32_e32 v3, v3
	v_sub_f32_e32 v5, v5, v35
	v_exp_f32_e32 v4, v4
	v_sub_f32_e32 v6, v6, v35
	v_exp_f32_e32 v5, v5
	v_sub_f32_e32 v7, v7, v35
	v_exp_f32_e32 v6, v6
	v_add_f32_e32 v34, 0, v2
	v_sub_f32_e32 v8, v8, v35
	v_exp_f32_e32 v7, v7
	v_add_f32_e32 v34, v3, v34
	v_sub_f32_e32 v9, v9, v35
	v_exp_f32_e32 v8, v8
	v_add_f32_e32 v34, v4, v34
	v_sub_f32_e32 v10, v10, v35
	v_exp_f32_e32 v9, v9
	v_add_f32_e32 v34, v5, v34
	v_sub_f32_e32 v11, v11, v35
	v_exp_f32_e32 v10, v10
	v_add_f32_e32 v34, v6, v34
	v_sub_f32_e32 v12, v12, v35
	v_exp_f32_e32 v11, v11
	v_add_f32_e32 v34, v7, v34
	v_sub_f32_e32 v13, v13, v35
	v_exp_f32_e32 v12, v12
	v_add_f32_e32 v34, v8, v34
	v_sub_f32_e32 v14, v14, v35
	v_exp_f32_e32 v13, v13
	v_add_f32_e32 v34, v9, v34
	v_sub_f32_e32 v15, v15, v35
	v_exp_f32_e32 v14, v14
	v_add_f32_e32 v34, v10, v34
	v_sub_f32_e32 v16, v16, v35
	v_exp_f32_e32 v15, v15
	v_add_f32_e32 v34, v11, v34
	v_sub_f32_e32 v17, v17, v35
	v_exp_f32_e32 v16, v16
	v_add_f32_e32 v34, v12, v34
	v_sub_f32_e32 v18, v18, v35
	v_exp_f32_e32 v17, v17
	v_add_f32_e32 v34, v13, v34
	v_sub_f32_e32 v19, v19, v35
	v_exp_f32_e32 v18, v18
	v_add_f32_e32 v34, v14, v34
	v_sub_f32_e32 v20, v20, v35
	v_exp_f32_e32 v19, v19
	v_add_f32_e32 v34, v15, v34
	v_sub_f32_e32 v21, v21, v35
	v_exp_f32_e32 v20, v20
	v_add_f32_e32 v34, v16, v34
	v_sub_f32_e32 v22, v22, v35
	v_exp_f32_e32 v21, v21
	v_add_f32_e32 v34, v17, v34
	v_sub_f32_e32 v23, v23, v35
	v_exp_f32_e32 v22, v22
	v_add_f32_e32 v34, v18, v34
	v_sub_f32_e32 v24, v24, v35
	v_exp_f32_e32 v23, v23
	v_add_f32_e32 v34, v19, v34
	v_sub_f32_e32 v25, v25, v35
	v_exp_f32_e32 v24, v24
	v_add_f32_e32 v34, v20, v34
	v_sub_f32_e32 v26, v26, v35
	v_exp_f32_e32 v25, v25
	v_add_f32_e32 v34, v21, v34
	v_sub_f32_e32 v27, v27, v35
	v_exp_f32_e32 v26, v26
	v_add_f32_e32 v34, v22, v34
	v_sub_f32_e32 v28, v28, v35
	v_exp_f32_e32 v27, v27
	v_add_f32_e32 v34, v23, v34
	v_sub_f32_e32 v29, v29, v35
	v_exp_f32_e32 v28, v28
	v_add_f32_e32 v34, v24, v34
	v_sub_f32_e32 v30, v30, v35
	v_exp_f32_e32 v29, v29
	v_add_f32_e32 v34, v25, v34
	v_sub_f32_e32 v31, v31, v35
	v_exp_f32_e32 v30, v30
	v_add_f32_e32 v34, v26, v34
	v_sub_f32_e32 v32, v32, v35
	v_exp_f32_e32 v31, v31
	v_add_f32_e32 v34, v27, v34
	v_sub_f32_e32 v33, v33, v35
	v_exp_f32_e32 v32, v32
	v_add_f32_e32 v34, v28, v34
	v_exp_f32_e32 v33, v33
	v_add_f32_e32 v34, v29, v34
	v_add_f32_e32 v34, v30, v34
	v_add_f32_e32 v34, v31, v34
	v_add_f32_e32 v34, v32, v34
	v_add_f32_e32 v34, v33, v34
	v_mov_b32_e32 v36, v34
	s_nop 1
	v_permlane32_swap_b32_e32 v34, v36
	v_add_f32_e32 v34, v34, v36
	v_pk_add_f32 v[202:203], v[34:35], 0 op_sel_hi:[1,0]
	v_cvt_pk_bf16_f32 v72, v2, v3
	v_cvt_pk_bf16_f32 v73, v4, v5
	v_cvt_pk_bf16_f32 v74, v6, v7
	v_cvt_pk_bf16_f32 v75, v8, v9
	v_cvt_pk_bf16_f32 v76, v10, v11
	s_nop 0
	v_xor_b32_e32 v66, 0x80000000, v203
	v_cvt_pk_bf16_f32 v77, v12, v13
	v_cvt_pk_bf16_f32 v78, v14, v15
	v_cvt_pk_bf16_f32 v79, v16, v17
	v_cvt_pk_bf16_f32 v80, v18, v19
	v_cvt_pk_bf16_f32 v81, v20, v21
	v_cvt_pk_bf16_f32 v82, v22, v23
	v_cvt_pk_bf16_f32 v83, v24, v25
	v_cvt_pk_bf16_f32 v84, v26, v27
	v_cvt_pk_bf16_f32 v85, v28, v29
	v_cvt_pk_bf16_f32 v86, v30, v31
	v_cvt_pk_bf16_f32 v87, v32, v33
	ds_read_b64_tr_b16 v[2:3], v237 offset:0
	ds_read_b64_tr_b16 v[4:5], v237 offset:0x800
	ds_read_b64_tr_b16 v[18:19], v237 offset:0x1000
	ds_read_b64_tr_b16 v[20:21], v237 offset:0x1800
	ds_read_b64_tr_b16 v[22:23], v237 offset:0x2000
	ds_read_b64_tr_b16 v[24:25], v237 offset:0x2800
	ds_read_b64_tr_b16 v[26:27], v237 offset:0x3000
	ds_read_b64_tr_b16 v[28:29], v237 offset:0x3800
	s_waitcnt lgkmcnt(0)
	s_nop 0
	v_mfma_f32_32x32x16_bf16 v[2:17], v[72:75], v[2:5], 0
	v_mfma_f32_32x32x16_bf16 v[2:17], v[76:79], v[18:21], v[2:17]
	ds_read_b64_tr_b16 v[18:19], v237 offset:0x200
	ds_read_b64_tr_b16 v[20:21], v237 offset:0xa00
	ds_read_b64_tr_b16 v[34:35], v237 offset:0x1200
	ds_read_b64_tr_b16 v[36:37], v237 offset:0x1a00
	ds_read_b64_tr_b16 v[38:39], v237 offset:0x2200
	ds_read_b64_tr_b16 v[40:41], v237 offset:0x2a00
	ds_read_b64_tr_b16 v[42:43], v237 offset:0x3200
	v_mfma_f32_32x32x16_bf16 v[2:17], v[80:83], v[22:25], v[2:17]
	ds_read_b64_tr_b16 v[44:45], v237 offset:0x3a00
	s_waitcnt lgkmcnt(0)
	v_mfma_f32_32x32x16_bf16 v[2:17], v[84:87], v[26:29], v[2:17]
	v_mfma_f32_32x32x16_bf16 v[18:33], v[72:75], v[18:21], 0
	v_mfma_f32_32x32x16_bf16 v[18:33], v[76:79], v[34:37], v[18:33]
	ds_read_b64_tr_b16 v[34:35], v237 offset:0x400
	ds_read_b64_tr_b16 v[36:37], v237 offset:0xc00
	ds_read_b64_tr_b16 v[88:89], v237 offset:0x1400
	ds_read_b64_tr_b16 v[90:91], v237 offset:0x1c00
	ds_read_b64_tr_b16 v[92:93], v237 offset:0x2400
	ds_read_b64_tr_b16 v[94:95], v237 offset:0x2c00
	ds_read_b64_tr_b16 v[96:97], v237 offset:0x3400
	v_mfma_f32_32x32x16_bf16 v[18:33], v[80:83], v[38:41], v[18:33]
	ds_read_b64_tr_b16 v[98:99], v237 offset:0x3c00
	s_waitcnt lgkmcnt(0)
	v_mfma_f32_32x32x16_bf16 v[18:33], v[84:87], v[42:45], v[18:33]
	v_mfma_f32_32x32x16_bf16 v[34:49], v[72:75], v[34:37], 0
	v_mfma_f32_32x32x16_bf16 v[34:49], v[76:79], v[88:91], v[34:49]
	ds_read_b64_tr_b16 v[88:89], v237 offset:0x600
	ds_read_b64_tr_b16 v[90:91], v237 offset:0xe00
	v_mfma_f32_32x32x16_bf16 v[34:49], v[80:83], v[92:95], v[34:49]
	ds_read_b64_tr_b16 v[92:93], v237 offset:0x1600
	ds_read_b64_tr_b16 v[94:95], v237 offset:0x1e00
	v_mfma_f32_32x32x16_bf16 v[34:49], v[84:87], v[96:99], v[34:49]
	ds_read_b64_tr_b16 v[96:97], v237 offset:0x2600
	ds_read_b64_tr_b16 v[98:99], v237 offset:0x2e00
	ds_read_b64_tr_b16 v[100:101], v237 offset:0x3600
	ds_read_b64_tr_b16 v[102:103], v237 offset:0x3e00
	s_waitcnt lgkmcnt(0)
	s_waitcnt vmcnt(1)
	ds_write_b128 v62, v[54:57] offset:16384
	s_waitcnt vmcnt(0)
	ds_write_b128 v63, v[58:61] offset:16384
	ds_write_b128 v64, v[50:53] offset:49152
	v_mfma_f32_32x32x16_bf16 v[50:65], v[72:75], v[88:91], 0
	ds_write_b128 v67, v[68:71] offset:49152
	s_addk_i32 s10, 0x80
	s_mov_b32 s14, 0
	s_movk_i32 s15, 0x4000
	v_mov_b32_e32 v67, v66
	v_mov_b32_e32 v68, v66
	v_mov_b32_e32 v69, v66
	v_mfma_f32_32x32x16_bf16 v[50:65], v[76:79], v[92:95], v[50:65]
	v_mov_b32_e32 v70, v66
	v_mov_b32_e32 v71, v66
	v_mov_b32_e32 v72, v66
	v_mov_b32_e32 v73, v66
	v_mov_b32_e32 v74, v66
	v_mov_b32_e32 v75, v66
	v_mov_b32_e32 v76, v66
	v_mfma_f32_32x32x16_bf16 v[50:65], v[80:83], v[96:99], v[50:65]
	v_mov_b32_e32 v77, v66
	v_mov_b32_e32 v78, v66
	v_mov_b32_e32 v79, v66
	v_mov_b32_e32 v80, v66
	v_mov_b32_e32 v81, v66
	s_waitcnt lgkmcnt(0)
	s_barrier
	v_mfma_f32_32x32x16_bf16 v[50:65], v[84:87], v[100:103], v[50:65]
	s_and_b32 s24, s22, 7
	s_lshl_b32 s24, s24, 6
	s_and_b32 s24, s24, 0x100
	s_mul_i32 s25, s10, 0x1400
	s_add_u32 s24, s24, s25
	s_add_u32 s24, s18, s24
	s_addc_u32 s25, s19, 0
	v_readlane_b32 s26, v254, 10
	s_nop 3
	s_lshl_b32 s26, s26, 5
	s_add_i32 s26, s26, 16
.LBB0_286:
	s_mov_b32 m0, s26
	s_nop 0
	global_load_lds_dwordx4 v250, s[24:25]
	s_add_i32 m0, s26, 0x400
	s_nop 0
	global_load_lds_dwordx4 v251, s[24:25]
	s_add_i32 m0, s26, 0x8000
	s_nop 0
	global_load_lds_dwordx4 v252, s[24:25]
	s_add_i32 m0, s26, 0x8400
	s_nop 0
	global_load_lds_dwordx4 v253, s[24:25]
	s_add_u32 s24, s24, 0x50000
	s_addc_u32 s25, s25, 0
	s_and_b32 s11, s15, 0x4000
	v_add_u32_e32 v90, s11, v227
	v_add_u32_e32 v86, v90, v228
	ds_read_b128 v[82:85], v86 offset:32768
	ds_read_b128 v[86:89], v86 offset:40960
	s_waitcnt lgkmcnt(1)
	v_mfma_f32_32x32x16_bf16 v[114:129], v[82:85], v[134:137], v[66:81]
	s_waitcnt lgkmcnt(0)
	v_mfma_f32_32x32x16_bf16 v[98:113], v[86:89], v[134:137], v[66:81]
	v_add_u32_e32 v86, v90, v229
	ds_read_b128 v[82:85], v86 offset:32768
	ds_read_b128 v[86:89], v86 offset:40960
	s_waitcnt lgkmcnt(1)
	v_mfma_f32_32x32x16_bf16 v[114:129], v[82:85], v[142:145], v[114:129]
	s_waitcnt lgkmcnt(0)
	v_mfma_f32_32x32x16_bf16 v[98:113], v[86:89], v[142:145], v[98:113]
	v_add_u32_e32 v86, v90, v230
	ds_read_b128 v[82:85], v86 offset:32768
	ds_read_b128 v[86:89], v86 offset:40960
	s_waitcnt lgkmcnt(1)
	v_mfma_f32_32x32x16_bf16 v[114:129], v[82:85], v[146:149], v[114:129]
	s_waitcnt lgkmcnt(0)
	v_mfma_f32_32x32x16_bf16 v[98:113], v[86:89], v[146:149], v[98:113]
	v_add_u32_e32 v86, v90, v231
	ds_read_b128 v[82:85], v86 offset:32768
	ds_read_b128 v[86:89], v86 offset:40960
	s_waitcnt lgkmcnt(1)
	v_mfma_f32_32x32x16_bf16 v[114:129], v[82:85], v[150:153], v[114:129]
	s_waitcnt lgkmcnt(0)
	v_mfma_f32_32x32x16_bf16 v[98:113], v[86:89], v[150:153], v[98:113]
	v_add_u32_e32 v86, v90, v232
	ds_read_b128 v[82:85], v86 offset:32768
	ds_read_b128 v[86:89], v86 offset:40960
	s_waitcnt lgkmcnt(1)
	v_mfma_f32_32x32x16_bf16 v[114:129], v[82:85], v[154:157], v[114:129]
	s_waitcnt lgkmcnt(0)
	v_mfma_f32_32x32x16_bf16 v[98:113], v[86:89], v[154:157], v[98:113]
	v_add_u32_e32 v86, v90, v233
	ds_read_b128 v[82:85], v86 offset:32768
	ds_read_b128 v[86:89], v86 offset:40960
	s_waitcnt lgkmcnt(1)
	v_mfma_f32_32x32x16_bf16 v[114:129], v[82:85], v[158:161], v[114:129]
	s_waitcnt lgkmcnt(0)
	v_mfma_f32_32x32x16_bf16 v[98:113], v[86:89], v[158:161], v[98:113]
	v_add_u32_e32 v86, v90, v234
	ds_read_b128 v[82:85], v86 offset:32768
	ds_read_b128 v[86:89], v86 offset:40960
	s_waitcnt lgkmcnt(1)
	v_mfma_f32_32x32x16_bf16 v[114:129], v[82:85], v[138:141], v[114:129]
	s_waitcnt lgkmcnt(0)
	v_mfma_f32_32x32x16_bf16 v[98:113], v[86:89], v[138:141], v[98:113]
	v_add_u32_e32 v86, v90, v235
	ds_read_b128 v[82:85], v86 offset:32768
	ds_read_b128 v[86:89], v86 offset:40960
	s_waitcnt lgkmcnt(1)
	v_mfma_f32_32x32x16_bf16 v[114:129], v[82:85], v[130:133], v[114:129]
	s_waitcnt lgkmcnt(0)
	v_mfma_f32_32x32x16_bf16 v[98:113], v[86:89], v[130:133], v[98:113]
	s_nop 9
	v_max_f32_e32 v82, v115, v115
	v_max_f32_e32 v83, v114, v114
	v_max_f32_e32 v82, v83, v82
	v_max3_f32 v82, v82, v116, v117
	v_max3_f32 v82, v82, v118, v119
	v_max3_f32 v82, v82, v120, v121
	v_max3_f32 v82, v82, v122, v123
	v_max3_f32 v82, v82, v124, v125
	v_max3_f32 v82, v82, v126, v127
	v_max3_f32 v82, v82, v128, v129
	v_max3_f32 v82, v82, v98, v99
	v_max3_f32 v82, v82, v100, v101
	v_max3_f32 v82, v82, v102, v103
	v_max3_f32 v82, v82, v104, v105
	v_max3_f32 v82, v82, v106, v107
	v_max3_f32 v82, v82, v108, v109
	v_max3_f32 v82, v82, v110, v111
	v_max3_f32 v82, v82, v112, v113
	v_mov_b32_e32 v83, v82
	s_nop 1
	v_permlane32_swap_b32_e32 v82, v83
	v_max_f32_e32 v83, v83, v83
	v_max_f32_e32 v82, v82, v82
	v_max_f32_e32 v82, v82, v83
	v_cmp_ge_f32_e32 vcc, s64, v82
	s_cmp_eq_u64 vcc, exec
	s_cbranch_scc0 .LBB0_294
	v_mov_b64_e32 v[96:97], v[80:81]
	v_mov_b32_e32 v195, 1.0
	v_mov_b64_e32 v[94:95], v[78:79]
	v_mov_b64_e32 v[92:93], v[76:77]
	v_mov_b64_e32 v[90:91], v[74:75]
	v_mov_b64_e32 v[88:89], v[72:73]
	v_mov_b64_e32 v[86:87], v[70:71]
	v_mov_b64_e32 v[84:85], v[68:69]
	v_mov_b64_e32 v[82:83], v[66:67]

.LBB0_292:
	v_add_f32_e32 v114, v114, v115
	v_fmac_f32_e32 v114, v202, v195
	v_add_u32_e32 v115, s11, v237
	ds_read_b64_tr_b16 v[116:117], v115 offset:0
	ds_read_b64_tr_b16 v[118:119], v115 offset:0x800
	ds_read_b64_tr_b16 v[120:121], v115 offset:0x1000
	ds_read_b64_tr_b16 v[122:123], v115 offset:0x1800
	ds_read_b64_tr_b16 v[124:125], v115 offset:0x2000
	ds_read_b64_tr_b16 v[126:127], v115 offset:0x2800
	ds_read_b64_tr_b16 v[238:239], v115 offset:0x3000
	ds_read_b64_tr_b16 v[240:241], v115 offset:0x3800
	s_waitcnt lgkmcnt(0)
	s_nop 0
	v_mfma_f32_32x32x16_bf16 v[2:17], v[110:113], v[116:119], v[2:17]
	ds_read_b64_tr_b16 v[116:117], v115 offset:0x200
	ds_read_b64_tr_b16 v[118:119], v115 offset:0xa00
	v_mfma_f32_32x32x16_bf16 v[2:17], v[106:109], v[120:123], v[2:17]
	ds_read_b64_tr_b16 v[120:121], v115 offset:0x1200
	ds_read_b64_tr_b16 v[122:123], v115 offset:0x1a00
	v_mfma_f32_32x32x16_bf16 v[2:17], v[102:105], v[124:127], v[2:17]
	ds_read_b64_tr_b16 v[124:125], v115 offset:0x2200
	ds_read_b64_tr_b16 v[126:127], v115 offset:0x2a00
	v_mfma_f32_32x32x16_bf16 v[2:17], v[98:101], v[238:241], v[2:17]
	ds_read_b64_tr_b16 v[238:239], v115 offset:0x3200
	ds_read_b64_tr_b16 v[240:241], v115 offset:0x3a00
	s_waitcnt lgkmcnt(0)
	v_mfma_f32_32x32x16_bf16 v[18:33], v[110:113], v[116:119], v[18:33]
	ds_read_b64_tr_b16 v[116:117], v115 offset:0x400
	ds_read_b64_tr_b16 v[118:119], v115 offset:0xc00
	v_mfma_f32_32x32x16_bf16 v[18:33], v[106:109], v[120:123], v[18:33]
	ds_read_b64_tr_b16 v[120:121], v115 offset:0x1400
	ds_read_b64_tr_b16 v[122:123], v115 offset:0x1c00
	v_mfma_f32_32x32x16_bf16 v[18:33], v[102:105], v[124:127], v[18:33]
	ds_read_b64_tr_b16 v[124:125], v115 offset:0x2400
	ds_read_b64_tr_b16 v[126:127], v115 offset:0x2c00
	v_mfma_f32_32x32x16_bf16 v[18:33], v[98:101], v[238:241], v[18:33]
	ds_read_b64_tr_b16 v[238:239], v115 offset:0x3400
	ds_read_b64_tr_b16 v[240:241], v115 offset:0x3c00
	s_waitcnt lgkmcnt(0)
	v_mfma_f32_32x32x16_bf16 v[34:49], v[110:113], v[116:119], v[34:49]
	ds_read_b64_tr_b16 v[116:117], v115 offset:0x600
	ds_read_b64_tr_b16 v[118:119], v115 offset:0xe00
	v_mfma_f32_32x32x16_bf16 v[34:49], v[106:109], v[120:123], v[34:49]
	ds_read_b64_tr_b16 v[120:121], v115 offset:0x1600
	ds_read_b64_tr_b16 v[122:123], v115 offset:0x1e00
	v_mfma_f32_32x32x16_bf16 v[34:49], v[102:105], v[124:127], v[34:49]
	ds_read_b64_tr_b16 v[124:125], v115 offset:0x2600
	ds_read_b64_tr_b16 v[126:127], v115 offset:0x2e00
	v_mfma_f32_32x32x16_bf16 v[34:49], v[98:101], v[238:241], v[34:49]
	ds_read_b64_tr_b16 v[238:239], v115 offset:0x3600
	ds_read_b64_tr_b16 v[240:241], v115 offset:0x3e00
	s_waitcnt lgkmcnt(0)
	v_mfma_f32_32x32x16_bf16 v[50:65], v[110:113], v[116:119], v[50:65]
	s_xor_b32 s11, s11, 0x4000
	s_add_i32 s11, s11, 16
	s_add_i32 s14, s14, 1
	s_addk_i32 s15, 0x4000
	s_add_i32 s10, s10, 64
	s_xor_b32 s26, s26, 0x4000
	s_cmp_eq_u32 s23, s14
	v_mfma_f32_32x32x16_bf16 v[50:65], v[106:109], v[120:123], v[50:65]
	s_waitcnt vmcnt(0)
	v_mfma_f32_32x32x16_bf16 v[50:65], v[102:105], v[124:127], v[50:65]
	s_barrier
	v_mfma_f32_32x32x16_bf16 v[50:65], v[98:101], v[238:241], v[50:65]
	s_cbranch_scc1 .LBB0_295
	v_mov_b32_e32 v202, v114
	s_branch .LBB0_286

.LBB0_314:
	v_lshl_or_b32 v0, v40, 2, v41
	v_ashrrev_i32_e32 v52, 1, v0
	v_mad_i64_i32 v[10:11], s[4:5], s2, v52, 0
	v_lshl_add_u64 v[30:31], v[10:11], 1, v[22:23]
	global_load_dwordx4 v[34:37], v[30:31], off offset:2048
	v_or_b32_e32 v48, 2, v52
	v_mad_i64_i32 v[10:11], s[4:5], s2, v48, 0
	v_or_b32_e32 v47, 4, v52
	v_lshl_add_u64 v[28:29], v[10:11], 1, v[22:23]
	v_mad_i64_i32 v[10:11], s[4:5], s2, v47, 0
	v_or_b32_e32 v0, 6, v52
	v_lshl_add_u64 v[26:27], v[10:11], 1, v[22:23]
	v_mad_i64_i32 v[10:11], s[4:5], s2, v0, 0
	v_lshl_add_u64 v[24:25], v[10:11], 1, v[22:23]
	s_waitcnt lgkmcnt(0)
	global_load_dwordx4 v[18:21], v[28:29], off offset:2048
	global_load_dwordx4 v[14:17], v[26:27], off offset:2048
	global_load_dwordx4 v[10:13], v[24:25], off offset:2048
	s_waitcnt vmcnt(0)
	v_and_b32_e32 v51, 0xffff0000, v34
	v_lshlrev_b32_e32 v49, 16, v34
	v_mul_f32_e32 v34, v51, v51
	v_and_b32_e32 v39, 0xffff0000, v35
	v_lshlrev_b32_e32 v38, 16, v35
	v_fmac_f32_e32 v34, v49, v49
	v_pk_mul_f32 v[32:33], v[38:39], v[38:39]
	v_and_b32_e32 v35, 0xffff0000, v36
	v_add_f32_e32 v32, v32, v34
	v_lshlrev_b32_e32 v34, 16, v36
	v_add_f32_e32 v50, v33, v32
	v_pk_mul_f32 v[32:33], v[34:35], v[34:35]
	s_nop 0
	v_add_f32_e32 v32, v32, v50
	v_add_f32_e32 v50, v33, v32
	v_and_b32_e32 v33, 0xffff0000, v37
	v_lshlrev_b32_e32 v32, 16, v37
	v_pk_mul_f32 v[36:37], v[32:33], v[32:33]
	s_nop 0
	v_add_f32_e32 v36, v36, v50
	v_add_f32_e32 v36, v37, v36
	ds_bpermute_b32 v37, v42, v36
	s_waitcnt lgkmcnt(0)
	v_add_f32_e32 v36, v36, v37
	ds_bpermute_b32 v37, v43, v36
	s_waitcnt lgkmcnt(0)
	v_add_f32_e32 v36, v36, v37
	ds_bpermute_b32 v37, v44, v36
	s_waitcnt lgkmcnt(0)
	v_add_f32_e32 v36, v36, v37
	ds_bpermute_b32 v37, v45, v36
	s_waitcnt lgkmcnt(0)
	v_add_f32_e32 v36, v36, v37
	v_fmamk_f32 v36, v36, 0x3c000000, v204
	v_cmp_gt_f32_e64 s[4:5], s49, v36
	v_mul_f32_e32 v37, 0x4b800000, v36
	s_nop 0
	v_cndmask_b32_e64 v36, v36, v37, s[4:5]
	v_rsq_f32_e32 v36, v36
	s_nop 0
	v_mul_f32_e32 v37, 0x45800000, v36
	v_cndmask_b32_e64 v50, v36, v37, s[4:5]
	v_mul_f32_e32 v36, v50, v49
	v_mul_f32_e32 v49, v2, v36
	v_mul_hi_i32 v36, v52, s57
	v_lshrrev_b32_e32 v37, 31, v36
	v_ashrrev_i32_e32 v36, 11, v36
	v_add_u32_e32 v36, v36, v37
	v_mul_i32_i24_e32 v36, 0x2100, v36
	v_sub_u32_e32 v36, v52, v36
	v_add_u32_e32 v37, 0xffffff00, v36
	v_cmp_lt_i32_e64 s[4:5], s62, v36
	v_and_b32_e32 v36, 63, v36
	v_ashrrev_i32_e32 v37, 6, v37
	v_cndmask_b32_e32 v36, v36, v37, vcc
	ds_bpermute_b32 v52, v44, v49
	v_lshlrev_b32_e32 v36, 5, v36
	v_cndmask_b32_e64 v36, 0, v36, s[4:5]
	v_or_b32_e32 v36, v36, v46
	v_ashrrev_i32_e32 v37, 31, v36
	v_lshl_add_u64 v[56:57], v[36:37], 3, s[12:13]
	global_load_dwordx4 v[60:63], v[56:57], off
	global_load_dwordx4 v[64:67], v[56:57], off offset:16
	global_load_dwordx4 v[68:71], v[56:57], off offset:32
	global_load_dwordx4 v[72:75], v[56:57], off offset:48
	s_and_saveexec_b64 s[14:15], s[4:5]
	s_cbranch_execz .LBB0_320
	s_waitcnt vmcnt(0)
	v_mov_b32_e32 v54, v60
	v_mov_b32_e32 v55, v61
	v_mul_f32_e32 v53, v49, v54
	s_waitcnt lgkmcnt(0)
	v_mul_f32_e32 v52, v55, v52
	s_and_saveexec_b64 s[16:17], s[6:7]
	s_xor_b64 s[16:17], exec, s[16:17]
	v_add_f32_e32 v49, v52, v53
	s_andn2_saveexec_b64 s[16:17], s[16:17]
	v_sub_f32_e32 v49, v53, v52
	s_or_b64 exec, exec, s[16:17]
.LBB0_320:
	s_or_b64 exec, exec, s[14:15]
	v_mul_f32_e32 v51, v50, v51
	v_mul_f32_e32 v51, v3, v51
	ds_bpermute_b32 v53, v44, v51
	s_and_saveexec_b64 s[14:15], s[4:5]
	s_cbranch_execz .LBB0_326
	v_mov_b32_e32 v54, v62
	v_mov_b32_e32 v55, v63
	s_waitcnt lgkmcnt(1)
	v_mul_f32_e32 v52, v51, v54
	s_waitcnt lgkmcnt(0)
	v_mul_f32_e32 v53, v55, v53
	s_and_saveexec_b64 s[16:17], s[6:7]
	s_xor_b64 s[16:17], exec, s[16:17]
	v_add_f32_e32 v51, v53, v52
	s_andn2_saveexec_b64 s[16:17], s[16:17]
	v_sub_f32_e32 v51, v52, v53
	s_or_b64 exec, exec, s[16:17]
.LBB0_326:
	s_or_b64 exec, exec, s[14:15]
	v_mul_f32_e32 v38, v50, v38
	v_mul_f32_e32 v38, v4, v38
	s_waitcnt lgkmcnt(0)
	ds_bpermute_b32 v53, v44, v38
	s_and_saveexec_b64 s[14:15], s[4:5]
	s_cbranch_execz .LBB0_332
	v_mov_b32_e32 v54, v64
	v_mov_b32_e32 v55, v65
	v_mul_f32_e32 v52, v38, v54
	s_waitcnt lgkmcnt(0)
	v_mul_f32_e32 v53, v55, v53
	s_and_saveexec_b64 s[16:17], s[6:7]
	s_xor_b64 s[16:17], exec, s[16:17]
	v_add_f32_e32 v38, v53, v52
	s_andn2_saveexec_b64 s[16:17], s[16:17]
	v_sub_f32_e32 v38, v52, v53
	s_or_b64 exec, exec, s[16:17]
.LBB0_332:
	s_or_b64 exec, exec, s[14:15]
	v_mul_f32_e32 v39, v50, v39
	v_mul_f32_e32 v39, v5, v39
	s_waitcnt lgkmcnt(0)
	ds_bpermute_b32 v53, v44, v39
	s_and_saveexec_b64 s[14:15], s[4:5]
	s_cbranch_execz .LBB0_338
	v_mov_b32_e32 v54, v66
	v_mov_b32_e32 v55, v67
	v_mul_f32_e32 v52, v39, v54
	s_waitcnt lgkmcnt(0)
	v_mul_f32_e32 v53, v55, v53
	s_and_saveexec_b64 s[16:17], s[6:7]
	s_xor_b64 s[16:17], exec, s[16:17]
	v_add_f32_e32 v39, v53, v52
	s_andn2_saveexec_b64 s[16:17], s[16:17]
	v_sub_f32_e32 v39, v52, v53
	s_or_b64 exec, exec, s[16:17]
.LBB0_338:
	s_or_b64 exec, exec, s[14:15]
	v_mul_f32_e32 v34, v50, v34
	v_mul_f32_e32 v34, v6, v34
	s_waitcnt lgkmcnt(0)
	ds_bpermute_b32 v53, v44, v34
	s_and_saveexec_b64 s[14:15], s[4:5]
	s_cbranch_execz .LBB0_344
	v_mov_b32_e32 v54, v68
	v_mov_b32_e32 v55, v69
	v_mul_f32_e32 v52, v34, v54
	s_waitcnt lgkmcnt(0)
	v_mul_f32_e32 v53, v55, v53
	s_and_saveexec_b64 s[16:17], s[6:7]
	s_xor_b64 s[16:17], exec, s[16:17]
	v_add_f32_e32 v34, v53, v52
	s_andn2_saveexec_b64 s[16:17], s[16:17]
	v_sub_f32_e32 v34, v52, v53
	s_or_b64 exec, exec, s[16:17]
.LBB0_344:
	s_or_b64 exec, exec, s[14:15]
	v_mul_f32_e32 v35, v50, v35
	v_mul_f32_e32 v35, v7, v35
	s_waitcnt lgkmcnt(0)
	ds_bpermute_b32 v53, v44, v35
	s_and_saveexec_b64 s[14:15], s[4:5]
	s_cbranch_execz .LBB0_350
	v_mov_b32_e32 v54, v70
	v_mov_b32_e32 v55, v71
	v_mul_f32_e32 v52, v35, v54
	s_waitcnt lgkmcnt(0)
	v_mul_f32_e32 v53, v55, v53
	s_and_saveexec_b64 s[16:17], s[6:7]
	s_xor_b64 s[16:17], exec, s[16:17]
	v_add_f32_e32 v35, v53, v52
	s_andn2_saveexec_b64 s[16:17], s[16:17]
	v_sub_f32_e32 v35, v52, v53
	s_or_b64 exec, exec, s[16:17]
.LBB0_350:
	s_or_b64 exec, exec, s[14:15]
	v_mul_f32_e32 v32, v50, v32
	v_mul_f32_e32 v32, v8, v32
	s_waitcnt lgkmcnt(0)
	ds_bpermute_b32 v53, v44, v32
	s_and_saveexec_b64 s[14:15], s[4:5]
	s_cbranch_execz .LBB0_356
	v_mov_b32_e32 v54, v72
	v_mov_b32_e32 v55, v73
	v_mul_f32_e32 v52, v32, v54
	s_waitcnt lgkmcnt(0)
	v_mul_f32_e32 v53, v55, v53
	s_and_saveexec_b64 s[16:17], s[6:7]
	s_xor_b64 s[16:17], exec, s[16:17]
	v_add_f32_e32 v32, v53, v52
	s_andn2_saveexec_b64 s[16:17], s[16:17]
	v_sub_f32_e32 v32, v52, v53
	s_or_b64 exec, exec, s[16:17]
.LBB0_356:
	s_or_b64 exec, exec, s[14:15]
	v_mul_f32_e32 v33, v50, v33
	v_mul_f32_e32 v33, v9, v33
	ds_bpermute_b32 v50, v44, v33
	s_and_saveexec_b64 s[14:15], s[4:5]
	s_cbranch_execz .LBB0_362
	v_mov_b32_e32 v36, v74
	v_mov_b32_e32 v37, v75
	v_mul_f32_e32 v36, v33, v36
	s_waitcnt lgkmcnt(0)
	v_mul_f32_e32 v37, v37, v50
	s_and_saveexec_b64 s[4:5], s[6:7]
	s_xor_b64 s[4:5], exec, s[4:5]
	v_add_f32_e32 v33, v37, v36
	s_andn2_saveexec_b64 s[4:5], s[4:5]
	v_sub_f32_e32 v33, v36, v37
	s_or_b64 exec, exec, s[4:5]
.LBB0_362:
	s_or_b64 exec, exec, s[14:15]
	v_cvt_pk_bf16_f32 v36, v49, v51
	v_cvt_pk_bf16_f32 v37, v38, v39
	v_cvt_pk_bf16_f32 v38, v34, v35
	v_cvt_pk_bf16_f32 v39, v32, v33
	global_store_dwordx4 v[30:31], v[36:39], off offset:2048
	s_waitcnt vmcnt(3)
	v_lshlrev_b32_e32 v34, 16, v18
	v_and_b32_e32 v33, 0xffff0000, v19
	v_and_b32_e32 v36, 0xffff0000, v18
	v_mul_f32_e32 v30, v36, v36
	v_lshlrev_b32_e32 v32, 16, v19
	v_fmac_f32_e32 v30, v34, v34
	v_pk_mul_f32 v[18:19], v[32:33], v[32:33]
	v_and_b32_e32 v31, 0xffff0000, v20
	v_add_f32_e32 v18, v18, v30
	v_lshlrev_b32_e32 v30, 16, v20
	v_add_f32_e32 v35, v19, v18
	v_pk_mul_f32 v[18:19], v[30:31], v[30:31]
	s_nop 0
	v_add_f32_e32 v18, v18, v35
	v_add_f32_e32 v35, v19, v18
	v_and_b32_e32 v19, 0xffff0000, v21
	v_lshlrev_b32_e32 v18, 16, v21
	v_pk_mul_f32 v[20:21], v[18:19], v[18:19]
	s_nop 0
	v_add_f32_e32 v20, v20, v35
	v_add_f32_e32 v20, v21, v20
	ds_bpermute_b32 v21, v42, v20
	s_waitcnt lgkmcnt(0)
	v_add_f32_e32 v20, v20, v21
	ds_bpermute_b32 v21, v43, v20
	s_waitcnt lgkmcnt(0)
	v_add_f32_e32 v20, v20, v21
	ds_bpermute_b32 v21, v44, v20
	s_waitcnt lgkmcnt(0)
	v_add_f32_e32 v20, v20, v21
	ds_bpermute_b32 v21, v45, v20
	s_waitcnt lgkmcnt(0)
	v_add_f32_e32 v20, v20, v21
	v_fmamk_f32 v20, v20, 0x3c000000, v204
	v_cmp_gt_f32_e64 s[4:5], s49, v20
	v_mul_f32_e32 v21, 0x4b800000, v20
	s_nop 0
	v_cndmask_b32_e64 v20, v20, v21, s[4:5]
	v_rsq_f32_e32 v20, v20
	s_nop 0
	v_mul_f32_e32 v21, 0x45800000, v20
	v_cndmask_b32_e64 v35, v20, v21, s[4:5]
	v_mul_f32_e32 v20, v35, v34
	v_mul_f32_e32 v34, v2, v20
	v_mul_hi_i32 v20, v48, s57
	v_lshrrev_b32_e32 v21, 31, v20
	v_ashrrev_i32_e32 v20, 11, v20
	v_add_u32_e32 v20, v20, v21
	v_mul_i32_i24_e32 v20, 0x2100, v20
	v_sub_u32_e32 v20, v48, v20
	v_add_u32_e32 v21, 0xffffff00, v20
	v_cmp_lt_i32_e64 s[4:5], s62, v20
	v_and_b32_e32 v20, 63, v20
	v_ashrrev_i32_e32 v21, 6, v21
	v_cndmask_b32_e32 v20, v20, v21, vcc
	ds_bpermute_b32 v37, v44, v34
	v_lshlrev_b32_e32 v20, 5, v20
	v_cndmask_b32_e64 v20, 0, v20, s[4:5]
	v_or_b32_e32 v20, v20, v46
	v_ashrrev_i32_e32 v21, 31, v20
	v_lshl_add_u64 v[56:57], v[20:21], 3, s[12:13]
	global_load_dwordx4 v[76:79], v[56:57], off
	global_load_dwordx4 v[80:83], v[56:57], off offset:16
	global_load_dwordx4 v[84:87], v[56:57], off offset:32
	global_load_dwordx4 v[88:91], v[56:57], off offset:48
	s_and_saveexec_b64 s[14:15], s[4:5]
	s_cbranch_execz .LBB0_368
	s_waitcnt vmcnt(0)
	v_mov_b32_e32 v38, v76
	v_mov_b32_e32 v39, v77
	v_mul_f32_e32 v38, v34, v38
	s_waitcnt lgkmcnt(0)
	v_mul_f32_e32 v37, v39, v37
	s_and_saveexec_b64 s[16:17], s[6:7]
	s_xor_b64 s[16:17], exec, s[16:17]
	v_add_f32_e32 v34, v37, v38
	s_andn2_saveexec_b64 s[16:17], s[16:17]
	v_sub_f32_e32 v34, v38, v37
	s_or_b64 exec, exec, s[16:17]
.LBB0_368:
	s_or_b64 exec, exec, s[14:15]
	v_mul_f32_e32 v36, v35, v36
	v_mul_f32_e32 v36, v3, v36
	ds_bpermute_b32 v38, v44, v36
	s_and_saveexec_b64 s[14:15], s[4:5]
	s_cbranch_execz .LBB0_374
	v_mov_b32_e32 v48, v78
	v_mov_b32_e32 v49, v79
	s_waitcnt lgkmcnt(1)
	v_mul_f32_e32 v37, v36, v48
	s_waitcnt lgkmcnt(0)
	v_mul_f32_e32 v38, v49, v38
	s_and_saveexec_b64 s[16:17], s[6:7]
	s_xor_b64 s[16:17], exec, s[16:17]
	v_add_f32_e32 v36, v38, v37
	s_andn2_saveexec_b64 s[16:17], s[16:17]
	v_sub_f32_e32 v36, v37, v38
	s_or_b64 exec, exec, s[16:17]
.LBB0_374:
	s_or_b64 exec, exec, s[14:15]
	v_mul_f32_e32 v32, v35, v32
	v_mul_f32_e32 v32, v4, v32
	s_waitcnt lgkmcnt(0)
	ds_bpermute_b32 v38, v44, v32
	s_and_saveexec_b64 s[14:15], s[4:5]
	s_cbranch_execz .LBB0_380
	v_mov_b32_e32 v48, v80
	v_mov_b32_e32 v49, v81
	v_mul_f32_e32 v37, v32, v48
	s_waitcnt lgkmcnt(0)
	v_mul_f32_e32 v38, v49, v38
	s_and_saveexec_b64 s[16:17], s[6:7]
	s_xor_b64 s[16:17], exec, s[16:17]
	v_add_f32_e32 v32, v38, v37
	s_andn2_saveexec_b64 s[16:17], s[16:17]
	v_sub_f32_e32 v32, v37, v38
	s_or_b64 exec, exec, s[16:17]
.LBB0_380:
	s_or_b64 exec, exec, s[14:15]
	v_mul_f32_e32 v33, v35, v33
	v_mul_f32_e32 v33, v5, v33
	s_waitcnt lgkmcnt(0)
	ds_bpermute_b32 v38, v44, v33
	s_and_saveexec_b64 s[14:15], s[4:5]
	s_cbranch_execz .LBB0_386
	v_mov_b32_e32 v48, v82
	v_mov_b32_e32 v49, v83
	v_mul_f32_e32 v37, v33, v48
	s_waitcnt lgkmcnt(0)
	v_mul_f32_e32 v38, v49, v38
	s_and_saveexec_b64 s[16:17], s[6:7]
	s_xor_b64 s[16:17], exec, s[16:17]
	v_add_f32_e32 v33, v38, v37
	s_andn2_saveexec_b64 s[16:17], s[16:17]
	v_sub_f32_e32 v33, v37, v38
	s_or_b64 exec, exec, s[16:17]
.LBB0_386:
	s_or_b64 exec, exec, s[14:15]
	v_mul_f32_e32 v30, v35, v30
	v_mul_f32_e32 v30, v6, v30
	s_waitcnt lgkmcnt(0)
	ds_bpermute_b32 v38, v44, v30
	s_and_saveexec_b64 s[14:15], s[4:5]
	s_cbranch_execz .LBB0_392
	v_mov_b32_e32 v48, v84
	v_mov_b32_e32 v49, v85
	v_mul_f32_e32 v37, v30, v48
	s_waitcnt lgkmcnt(0)
	v_mul_f32_e32 v38, v49, v38
	s_and_saveexec_b64 s[16:17], s[6:7]
	s_xor_b64 s[16:17], exec, s[16:17]
	v_add_f32_e32 v30, v38, v37
	s_andn2_saveexec_b64 s[16:17], s[16:17]
	v_sub_f32_e32 v30, v37, v38
	s_or_b64 exec, exec, s[16:17]
.LBB0_392:
	s_or_b64 exec, exec, s[14:15]
	v_mul_f32_e32 v31, v35, v31
	v_mul_f32_e32 v31, v7, v31
	s_waitcnt lgkmcnt(0)
	ds_bpermute_b32 v38, v44, v31
	s_and_saveexec_b64 s[14:15], s[4:5]
	s_cbranch_execz .LBB0_398
	v_mov_b32_e32 v48, v86
	v_mov_b32_e32 v49, v87
	v_mul_f32_e32 v37, v31, v48
	s_waitcnt lgkmcnt(0)
	v_mul_f32_e32 v38, v49, v38
	s_and_saveexec_b64 s[16:17], s[6:7]
	s_xor_b64 s[16:17], exec, s[16:17]
	v_add_f32_e32 v31, v38, v37
	s_andn2_saveexec_b64 s[16:17], s[16:17]
	v_sub_f32_e32 v31, v37, v38
	s_or_b64 exec, exec, s[16:17]
.LBB0_398:
	s_or_b64 exec, exec, s[14:15]
	v_mul_f32_e32 v18, v35, v18
	v_mul_f32_e32 v18, v8, v18
	s_waitcnt lgkmcnt(0)
	ds_bpermute_b32 v38, v44, v18
	s_and_saveexec_b64 s[14:15], s[4:5]
	s_cbranch_execz .LBB0_404
	v_mov_b32_e32 v48, v88
	v_mov_b32_e32 v49, v89
	v_mul_f32_e32 v37, v18, v48
	s_waitcnt lgkmcnt(0)
	v_mul_f32_e32 v38, v49, v38
	s_and_saveexec_b64 s[16:17], s[6:7]
	s_xor_b64 s[16:17], exec, s[16:17]
	v_add_f32_e32 v18, v38, v37
	s_andn2_saveexec_b64 s[16:17], s[16:17]
	v_sub_f32_e32 v18, v37, v38
	s_or_b64 exec, exec, s[16:17]
.LBB0_404:
	s_or_b64 exec, exec, s[14:15]
	v_mul_f32_e32 v19, v35, v19
	v_mul_f32_e32 v19, v9, v19
	ds_bpermute_b32 v35, v44, v19
	s_and_saveexec_b64 s[14:15], s[4:5]
	s_cbranch_execz .LBB0_410
	v_mov_b32_e32 v20, v90
	v_mov_b32_e32 v21, v91
	v_mul_f32_e32 v20, v19, v20
	s_waitcnt lgkmcnt(0)
	v_mul_f32_e32 v21, v21, v35
	s_and_saveexec_b64 s[4:5], s[6:7]
	s_xor_b64 s[4:5], exec, s[4:5]
	v_add_f32_e32 v19, v21, v20
	s_andn2_saveexec_b64 s[4:5], s[4:5]
	v_sub_f32_e32 v19, v20, v21
	s_or_b64 exec, exec, s[4:5]
.LBB0_410:
	s_or_b64 exec, exec, s[14:15]
	v_cvt_pk_bf16_f32 v34, v34, v36
	s_waitcnt lgkmcnt(0)
	v_cvt_pk_bf16_f32 v35, v32, v33
	v_cvt_pk_bf16_f32 v36, v30, v31
	s_waitcnt vmcnt(2)
	v_and_b32_e32 v30, 0xffff0000, v14
	v_cvt_pk_bf16_f32 v37, v18, v19
	global_store_dwordx4 v[28:29], v[34:37], off offset:2048
	v_lshlrev_b32_e32 v28, 16, v14
	v_mul_f32_e32 v18, v30, v30
	v_and_b32_e32 v21, 0xffff0000, v15
	v_lshlrev_b32_e32 v20, 16, v15
	v_fmac_f32_e32 v18, v28, v28
	v_pk_mul_f32 v[14:15], v[20:21], v[20:21]
	v_and_b32_e32 v19, 0xffff0000, v16
	v_add_f32_e32 v14, v14, v18
	v_lshlrev_b32_e32 v18, 16, v16
	v_add_f32_e32 v29, v15, v14
	v_pk_mul_f32 v[14:15], v[18:19], v[18:19]
	s_nop 0
	v_add_f32_e32 v14, v14, v29
	v_add_f32_e32 v29, v15, v14
	v_and_b32_e32 v15, 0xffff0000, v17
	v_lshlrev_b32_e32 v14, 16, v17
	v_pk_mul_f32 v[16:17], v[14:15], v[14:15]
	s_nop 0
	v_add_f32_e32 v16, v16, v29
	v_add_f32_e32 v16, v17, v16
	ds_bpermute_b32 v17, v42, v16
	s_waitcnt lgkmcnt(0)
	v_add_f32_e32 v16, v16, v17
	ds_bpermute_b32 v17, v43, v16
	s_waitcnt lgkmcnt(0)
	v_add_f32_e32 v16, v16, v17
	ds_bpermute_b32 v17, v44, v16
	s_waitcnt lgkmcnt(0)
	v_add_f32_e32 v16, v16, v17
	ds_bpermute_b32 v17, v45, v16
	s_waitcnt lgkmcnt(0)
	v_add_f32_e32 v16, v16, v17
	v_fmamk_f32 v16, v16, 0x3c000000, v204
	v_cmp_gt_f32_e64 s[4:5], s49, v16
	v_mul_f32_e32 v17, 0x4b800000, v16
	s_nop 0
	v_cndmask_b32_e64 v16, v16, v17, s[4:5]
	v_rsq_f32_e32 v16, v16
	s_nop 0
	v_mul_f32_e32 v17, 0x45800000, v16
	v_cndmask_b32_e64 v29, v16, v17, s[4:5]
	v_mul_f32_e32 v16, v29, v28
	v_mul_f32_e32 v28, v2, v16
	v_mul_hi_i32 v16, v47, s57
	v_lshrrev_b32_e32 v17, 31, v16
	v_ashrrev_i32_e32 v16, 11, v16
	v_add_u32_e32 v16, v16, v17
	v_mul_i32_i24_e32 v16, 0x2100, v16
	v_sub_u32_e32 v16, v47, v16
	v_add_u32_e32 v17, 0xffffff00, v16
	v_cmp_lt_i32_e64 s[4:5], s62, v16
	v_and_b32_e32 v16, 63, v16
	v_ashrrev_i32_e32 v17, 6, v17
	v_cndmask_b32_e32 v16, v16, v17, vcc
	ds_bpermute_b32 v31, v44, v28
	v_lshlrev_b32_e32 v16, 5, v16
	v_cndmask_b32_e64 v16, 0, v16, s[4:5]
	v_or_b32_e32 v16, v16, v46
	v_ashrrev_i32_e32 v17, 31, v16
	v_lshl_add_u64 v[56:57], v[16:17], 3, s[12:13]
	global_load_dwordx4 v[92:95], v[56:57], off
	global_load_dwordx4 v[96:99], v[56:57], off offset:16
	global_load_dwordx4 v[100:103], v[56:57], off offset:32
	global_load_dwordx4 v[104:107], v[56:57], off offset:48
	s_and_saveexec_b64 s[14:15], s[4:5]
	s_cbranch_execz .LBB0_416
	s_waitcnt vmcnt(0)
	v_mov_b32_e32 v32, v92
	v_mov_b32_e32 v33, v93
	v_mul_f32_e32 v32, v28, v32
	s_waitcnt lgkmcnt(0)
	v_mul_f32_e32 v31, v33, v31
	s_and_saveexec_b64 s[16:17], s[6:7]
	s_xor_b64 s[16:17], exec, s[16:17]
	v_add_f32_e32 v28, v31, v32
	s_andn2_saveexec_b64 s[16:17], s[16:17]
	v_sub_f32_e32 v28, v32, v31
	s_or_b64 exec, exec, s[16:17]
.LBB0_416:
	s_or_b64 exec, exec, s[14:15]
	v_mul_f32_e32 v30, v29, v30
	v_mul_f32_e32 v30, v3, v30
	ds_bpermute_b32 v32, v44, v30
	s_and_saveexec_b64 s[14:15], s[4:5]
	s_cbranch_execz .LBB0_422
	v_mov_b32_e32 v34, v94
	v_mov_b32_e32 v35, v95
	s_waitcnt lgkmcnt(1)
	v_mul_f32_e32 v31, v30, v34
	s_waitcnt lgkmcnt(0)
	v_mul_f32_e32 v32, v35, v32
	s_and_saveexec_b64 s[16:17], s[6:7]
	s_xor_b64 s[16:17], exec, s[16:17]
	v_add_f32_e32 v30, v32, v31
	s_andn2_saveexec_b64 s[16:17], s[16:17]
	v_sub_f32_e32 v30, v31, v32
	s_or_b64 exec, exec, s[16:17]
.LBB0_422:
	s_or_b64 exec, exec, s[14:15]
	v_mul_f32_e32 v20, v29, v20
	v_mul_f32_e32 v20, v4, v20
	s_waitcnt lgkmcnt(0)
	ds_bpermute_b32 v32, v44, v20
	s_and_saveexec_b64 s[14:15], s[4:5]
	s_cbranch_execz .LBB0_428
	v_mov_b32_e32 v34, v96
	v_mov_b32_e32 v35, v97
	v_mul_f32_e32 v31, v20, v34
	s_waitcnt lgkmcnt(0)
	v_mul_f32_e32 v32, v35, v32
	s_and_saveexec_b64 s[16:17], s[6:7]
	s_xor_b64 s[16:17], exec, s[16:17]
	v_add_f32_e32 v20, v32, v31
	s_andn2_saveexec_b64 s[16:17], s[16:17]
	v_sub_f32_e32 v20, v31, v32
	s_or_b64 exec, exec, s[16:17]
.LBB0_428:
	s_or_b64 exec, exec, s[14:15]
	v_mul_f32_e32 v21, v29, v21
	v_mul_f32_e32 v21, v5, v21
	s_waitcnt lgkmcnt(0)
	ds_bpermute_b32 v32, v44, v21
	s_and_saveexec_b64 s[14:15], s[4:5]
	s_cbranch_execz .LBB0_434
	v_mov_b32_e32 v34, v98
	v_mov_b32_e32 v35, v99
	v_mul_f32_e32 v31, v21, v34
	s_waitcnt lgkmcnt(0)
	v_mul_f32_e32 v32, v35, v32
	s_and_saveexec_b64 s[16:17], s[6:7]
	s_xor_b64 s[16:17], exec, s[16:17]
	v_add_f32_e32 v21, v32, v31
	s_andn2_saveexec_b64 s[16:17], s[16:17]
	v_sub_f32_e32 v21, v31, v32
	s_or_b64 exec, exec, s[16:17]
.LBB0_434:
	s_or_b64 exec, exec, s[14:15]
	v_mul_f32_e32 v18, v29, v18
	v_mul_f32_e32 v18, v6, v18
	s_waitcnt lgkmcnt(0)
	ds_bpermute_b32 v32, v44, v18
	s_and_saveexec_b64 s[14:15], s[4:5]
	s_cbranch_execz .LBB0_440
	v_mov_b32_e32 v34, v100
	v_mov_b32_e32 v35, v101
	v_mul_f32_e32 v31, v18, v34
	s_waitcnt lgkmcnt(0)
	v_mul_f32_e32 v32, v35, v32
	s_and_saveexec_b64 s[16:17], s[6:7]
	s_xor_b64 s[16:17], exec, s[16:17]
	v_add_f32_e32 v18, v32, v31
	s_andn2_saveexec_b64 s[16:17], s[16:17]
	v_sub_f32_e32 v18, v31, v32
	s_or_b64 exec, exec, s[16:17]
.LBB0_440:
	s_or_b64 exec, exec, s[14:15]
	v_mul_f32_e32 v19, v29, v19
	v_mul_f32_e32 v19, v7, v19
	s_waitcnt lgkmcnt(0)
	ds_bpermute_b32 v32, v44, v19
	s_and_saveexec_b64 s[14:15], s[4:5]
	s_cbranch_execz .LBB0_446
	v_mov_b32_e32 v34, v102
	v_mov_b32_e32 v35, v103
	v_mul_f32_e32 v31, v19, v34
	s_waitcnt lgkmcnt(0)
	v_mul_f32_e32 v32, v35, v32
	s_and_saveexec_b64 s[16:17], s[6:7]
	s_xor_b64 s[16:17], exec, s[16:17]
	v_add_f32_e32 v19, v32, v31
	s_andn2_saveexec_b64 s[16:17], s[16:17]
	v_sub_f32_e32 v19, v31, v32
	s_or_b64 exec, exec, s[16:17]
.LBB0_446:
	s_or_b64 exec, exec, s[14:15]
	v_mul_f32_e32 v14, v29, v14
	v_mul_f32_e32 v14, v8, v14
	s_waitcnt lgkmcnt(0)
	ds_bpermute_b32 v32, v44, v14
	s_and_saveexec_b64 s[14:15], s[4:5]
	s_cbranch_execz .LBB0_452
	v_mov_b32_e32 v34, v104
	v_mov_b32_e32 v35, v105
	v_mul_f32_e32 v31, v14, v34
	s_waitcnt lgkmcnt(0)
	v_mul_f32_e32 v32, v35, v32
	s_and_saveexec_b64 s[16:17], s[6:7]
	s_xor_b64 s[16:17], exec, s[16:17]
	v_add_f32_e32 v14, v32, v31
	s_andn2_saveexec_b64 s[16:17], s[16:17]
	v_sub_f32_e32 v14, v31, v32
	s_or_b64 exec, exec, s[16:17]
.LBB0_452:
	s_or_b64 exec, exec, s[14:15]
	v_mul_f32_e32 v15, v29, v15
	v_mul_f32_e32 v15, v9, v15
	ds_bpermute_b32 v29, v44, v15
	s_and_saveexec_b64 s[14:15], s[4:5]
	s_cbranch_execz .LBB0_458
	v_mov_b32_e32 v16, v106
	v_mov_b32_e32 v17, v107
	v_mul_f32_e32 v16, v15, v16
	s_waitcnt lgkmcnt(0)
	v_mul_f32_e32 v17, v17, v29
	s_and_saveexec_b64 s[4:5], s[6:7]
	s_xor_b64 s[4:5], exec, s[4:5]
	v_add_f32_e32 v15, v17, v16
	s_andn2_saveexec_b64 s[4:5], s[4:5]
	v_sub_f32_e32 v15, v16, v17
	s_or_b64 exec, exec, s[4:5]
.LBB0_458:
	s_or_b64 exec, exec, s[14:15]
	v_cvt_pk_bf16_f32 v16, v28, v30
	v_cvt_pk_bf16_f32 v17, v20, v21
	v_cvt_pk_bf16_f32 v18, v18, v19
	s_waitcnt vmcnt(2)
	v_and_b32_e32 v20, 0xffff0000, v10
	v_cvt_pk_bf16_f32 v19, v14, v15
	global_store_dwordx4 v[26:27], v[16:19], off offset:2048
	v_mul_f32_e32 v14, v20, v20
	v_and_b32_e32 v15, 0xffff0000, v12
	v_lshlrev_b32_e32 v18, 16, v10
	v_and_b32_e32 v17, 0xffff0000, v11
	v_lshlrev_b32_e32 v16, 16, v11
	v_fmac_f32_e32 v14, v18, v18
	v_pk_mul_f32 v[10:11], v[16:17], v[16:17]
	s_nop 0
	v_add_f32_e32 v10, v10, v14
	v_lshlrev_b32_e32 v14, 16, v12
	v_add_f32_e32 v19, v11, v10
	v_pk_mul_f32 v[10:11], v[14:15], v[14:15]
	s_nop 0
	v_add_f32_e32 v10, v10, v19
	v_add_f32_e32 v19, v11, v10
	v_and_b32_e32 v11, 0xffff0000, v13
	v_lshlrev_b32_e32 v10, 16, v13
	v_pk_mul_f32 v[12:13], v[10:11], v[10:11]
	s_nop 0
	v_add_f32_e32 v12, v12, v19
	v_add_f32_e32 v12, v13, v12
	ds_bpermute_b32 v13, v42, v12
	s_waitcnt lgkmcnt(0)
	v_add_f32_e32 v12, v12, v13
	ds_bpermute_b32 v13, v43, v12
	s_waitcnt lgkmcnt(0)
	v_add_f32_e32 v12, v12, v13
	ds_bpermute_b32 v13, v44, v12
	s_waitcnt lgkmcnt(0)
	v_add_f32_e32 v12, v12, v13
	ds_bpermute_b32 v13, v45, v12
	s_waitcnt lgkmcnt(0)
	v_add_f32_e32 v12, v12, v13
	v_fmamk_f32 v12, v12, 0x3c000000, v204
	v_cmp_gt_f32_e64 s[4:5], s49, v12
	v_mul_f32_e32 v13, 0x4b800000, v12
	s_nop 0
	v_cndmask_b32_e64 v12, v12, v13, s[4:5]
	v_rsq_f32_e32 v12, v12
	s_nop 0
	v_mul_f32_e32 v13, 0x45800000, v12
	v_cndmask_b32_e64 v19, v12, v13, s[4:5]
	v_mul_f32_e32 v12, v19, v18
	v_mul_f32_e32 v18, v2, v12
	v_mul_hi_i32 v12, v0, s57
	v_lshrrev_b32_e32 v13, 31, v12
	v_ashrrev_i32_e32 v12, 11, v12
	v_add_u32_e32 v12, v12, v13
	v_mul_i32_i24_e32 v12, 0x2100, v12
	v_sub_u32_e32 v0, v0, v12
	v_add_u32_e32 v12, 0xffffff00, v0
	v_cmp_lt_i32_e64 s[4:5], s62, v0
	v_and_b32_e32 v0, 63, v0
	v_ashrrev_i32_e32 v12, 6, v12
	v_cndmask_b32_e32 v0, v0, v12, vcc
	v_lshlrev_b32_e32 v0, 5, v0
	v_cndmask_b32_e64 v0, 0, v0, s[4:5]
	v_or_b32_e32 v12, v0, v46
	ds_bpermute_b32 v0, v44, v18
	v_ashrrev_i32_e32 v13, 31, v12
	v_lshl_add_u64 v[56:57], v[12:13], 3, s[12:13]
	global_load_dwordx4 v[108:111], v[56:57], off
	global_load_dwordx4 v[112:115], v[56:57], off offset:16
	global_load_dwordx4 v[116:119], v[56:57], off offset:32
	global_load_dwordx4 v[120:123], v[56:57], off offset:48
	s_and_saveexec_b64 s[14:15], s[4:5]
	s_cbranch_execz .LBB0_464
	s_waitcnt vmcnt(0)
	v_mov_b32_e32 v26, v108
	v_mov_b32_e32 v27, v109
	v_mul_f32_e32 v21, v18, v26
	s_waitcnt lgkmcnt(0)
	v_mul_f32_e32 v0, v27, v0
	s_and_saveexec_b64 s[16:17], s[6:7]
	s_xor_b64 s[16:17], exec, s[16:17]
	v_add_f32_e32 v18, v0, v21
	s_andn2_saveexec_b64 s[16:17], s[16:17]
	v_sub_f32_e32 v18, v21, v0
	s_or_b64 exec, exec, s[16:17]
.LBB0_464:
	s_or_b64 exec, exec, s[14:15]
	s_waitcnt lgkmcnt(0)
	v_mul_f32_e32 v0, v19, v20
	v_mul_f32_e32 v0, v3, v0
	ds_bpermute_b32 v21, v44, v0
	s_and_saveexec_b64 s[14:15], s[4:5]
	s_cbranch_execz .LBB0_470
	v_mov_b32_e32 v26, v110
	v_mov_b32_e32 v27, v111
	v_mul_f32_e32 v20, v0, v26
	s_waitcnt lgkmcnt(0)
	v_mul_f32_e32 v21, v27, v21
	s_and_saveexec_b64 s[16:17], s[6:7]
	s_xor_b64 s[16:17], exec, s[16:17]
	v_add_f32_e32 v0, v21, v20
	s_andn2_saveexec_b64 s[16:17], s[16:17]
	v_sub_f32_e32 v0, v20, v21
	s_or_b64 exec, exec, s[16:17]
.LBB0_470:
	s_or_b64 exec, exec, s[14:15]
	v_mul_f32_e32 v16, v19, v16
	v_mul_f32_e32 v16, v4, v16
	s_waitcnt lgkmcnt(0)
	ds_bpermute_b32 v21, v44, v16
	s_and_saveexec_b64 s[14:15], s[4:5]
	s_cbranch_execz .LBB0_476
	v_mov_b32_e32 v26, v112
	v_mov_b32_e32 v27, v113
	v_mul_f32_e32 v20, v16, v26
	s_waitcnt lgkmcnt(0)
	v_mul_f32_e32 v21, v27, v21
	s_and_saveexec_b64 s[16:17], s[6:7]
	s_xor_b64 s[16:17], exec, s[16:17]
	v_add_f32_e32 v16, v21, v20
	s_andn2_saveexec_b64 s[16:17], s[16:17]
	v_sub_f32_e32 v16, v20, v21
	s_or_b64 exec, exec, s[16:17]
.LBB0_476:
	s_or_b64 exec, exec, s[14:15]
	v_mul_f32_e32 v17, v19, v17
	v_mul_f32_e32 v17, v5, v17
	s_waitcnt lgkmcnt(0)
	ds_bpermute_b32 v21, v44, v17
	s_and_saveexec_b64 s[14:15], s[4:5]
	s_cbranch_execz .LBB0_482
	v_mov_b32_e32 v26, v114
	v_mov_b32_e32 v27, v115
	v_mul_f32_e32 v20, v17, v26
	s_waitcnt lgkmcnt(0)
	v_mul_f32_e32 v21, v27, v21
	s_and_saveexec_b64 s[16:17], s[6:7]
	s_xor_b64 s[16:17], exec, s[16:17]
	v_add_f32_e32 v17, v21, v20
	s_andn2_saveexec_b64 s[16:17], s[16:17]
	v_sub_f32_e32 v17, v20, v21
	s_or_b64 exec, exec, s[16:17]
.LBB0_482:
	s_or_b64 exec, exec, s[14:15]
	v_mul_f32_e32 v14, v19, v14
	v_mul_f32_e32 v14, v6, v14
	s_waitcnt lgkmcnt(0)
	ds_bpermute_b32 v21, v44, v14
	s_and_saveexec_b64 s[14:15], s[4:5]
	s_cbranch_execz .LBB0_488
	v_mov_b32_e32 v26, v116
	v_mov_b32_e32 v27, v117
	v_mul_f32_e32 v20, v14, v26
	s_waitcnt lgkmcnt(0)
	v_mul_f32_e32 v21, v27, v21
	s_and_saveexec_b64 s[16:17], s[6:7]
	s_xor_b64 s[16:17], exec, s[16:17]
	v_add_f32_e32 v14, v21, v20
	s_andn2_saveexec_b64 s[16:17], s[16:17]
	v_sub_f32_e32 v14, v20, v21
	s_or_b64 exec, exec, s[16:17]
.LBB0_488:
	s_or_b64 exec, exec, s[14:15]
	v_mul_f32_e32 v15, v19, v15
	v_mul_f32_e32 v15, v7, v15
	s_waitcnt lgkmcnt(0)
	ds_bpermute_b32 v21, v44, v15
	s_and_saveexec_b64 s[14:15], s[4:5]
	s_cbranch_execz .LBB0_494
	v_mov_b32_e32 v26, v118
	v_mov_b32_e32 v27, v119
	v_mul_f32_e32 v20, v15, v26
	s_waitcnt lgkmcnt(0)
	v_mul_f32_e32 v21, v27, v21
	s_and_saveexec_b64 s[16:17], s[6:7]
	s_xor_b64 s[16:17], exec, s[16:17]
	v_add_f32_e32 v15, v21, v20
	s_andn2_saveexec_b64 s[16:17], s[16:17]
	v_sub_f32_e32 v15, v20, v21
	s_or_b64 exec, exec, s[16:17]
.LBB0_494:
	s_or_b64 exec, exec, s[14:15]
	v_mul_f32_e32 v10, v19, v10
	v_mul_f32_e32 v10, v8, v10
	s_waitcnt lgkmcnt(0)
	ds_bpermute_b32 v21, v44, v10
	s_and_saveexec_b64 s[14:15], s[4:5]
	s_cbranch_execz .LBB0_500
	v_mov_b32_e32 v26, v120
	v_mov_b32_e32 v27, v121
	v_mul_f32_e32 v20, v10, v26
	s_waitcnt lgkmcnt(0)
	v_mul_f32_e32 v21, v27, v21
	s_and_saveexec_b64 s[16:17], s[6:7]
	s_xor_b64 s[16:17], exec, s[16:17]
	v_add_f32_e32 v10, v21, v20
	s_andn2_saveexec_b64 s[16:17], s[16:17]
	v_sub_f32_e32 v10, v20, v21
	s_or_b64 exec, exec, s[16:17]
.LBB0_500:
	s_or_b64 exec, exec, s[14:15]
	v_mul_f32_e32 v11, v19, v11
	v_mul_f32_e32 v11, v9, v11
	ds_bpermute_b32 v19, v44, v11
	s_and_saveexec_b64 s[14:15], s[4:5]
	s_cbranch_execz .LBB0_313
	v_mov_b32_e32 v12, v122
	v_mov_b32_e32 v13, v123
	v_mul_f32_e32 v12, v11, v12
	s_waitcnt lgkmcnt(0)
	v_mul_f32_e32 v13, v13, v19
	s_and_saveexec_b64 s[4:5], s[6:7]
	s_xor_b64 s[4:5], exec, s[4:5]
	v_add_f32_e32 v11, v13, v12
	s_andn2_saveexec_b64 s[4:5], s[4:5]
	s_cbranch_execz .LBB0_312
	v_sub_f32_e32 v11, v12, v13
	s_branch .LBB0_312

.LBB0_514:
	v_lshl_or_b32 v172, s69, 8, v175
	v_ashrrev_i32_e32 v173, 31, v172
	v_lshl_add_u64 v[252:253], v[172:173], 2, s[34:35]
	global_load_dwordx4 v[142:145], v[252:253], off
	global_load_dwordx4 v[138:141], v[252:253], off offset:16
	global_load_dwordx4 v[134:137], v[252:253], off offset:512
	global_load_dwordx4 v[130:133], v[252:253], off offset:528
	v_add_lshl_u32 v180, v152, v172, 2
	v_add_lshl_u32 v181, v154, v172, 2
	v_add_lshl_u32 v182, v156, v172, 2
	v_add_lshl_u32 v183, v158, v172, 2
	v_add_lshl_u32 v184, v160, v172, 2
	v_add_lshl_u32 v185, v162, v172, 2
	v_add_lshl_u32 v186, v164, v172, 2
	v_add_lshl_u32 v187, v166, v172, 2
	s_and_b64 vcc, exec, s[6:7]
	s_mov_b32 s69, s22
	s_mov_b32 s36, s67
	s_mov_b64 s[30:31], s[26:27]
	global_load_dwordx4 v[188:191], v180, s[4:5]
	global_load_dwordx4 v[192:195], v180, s[4:5] offset:16
	global_load_dwordx4 v[196:199], v180, s[4:5] offset:512
	global_load_dwordx4 v[200:203], v180, s[4:5] offset:528
	global_load_dwordx4 v[220:223], v181, s[4:5]
	global_load_dwordx4 v[224:227], v181, s[4:5] offset:16
	global_load_dwordx4 v[228:231], v181, s[4:5] offset:512
	global_load_dwordx4 v[232:235], v181, s[4:5] offset:528
	global_load_dwordx4 v[236:239], v182, s[4:5]
	global_load_dwordx4 v[240:243], v182, s[4:5] offset:16
	global_load_dwordx4 v[244:247], v182, s[4:5] offset:512
	global_load_dwordx4 v[248:251], v182, s[4:5] offset:528
	s_waitcnt vmcnt(11)
	v_pk_fma_f32 v[190:191], v[128:129], v[144:145], v[190:191]
	v_pk_fma_f32 v[188:189], v[126:127], v[142:143], v[188:189]
	global_store_dwordx4 v180, v[188:191], s[28:29]
	global_load_dwordx4 v[188:191], v183, s[4:5]
	s_waitcnt vmcnt(12)
	v_pk_fma_f32 v[194:195], v[124:125], v[140:141], v[194:195]
	v_pk_fma_f32 v[192:193], v[122:123], v[138:139], v[192:193]
	global_store_dwordx4 v180, v[192:195], s[28:29] offset:16
	global_load_dwordx4 v[192:195], v183, s[4:5] offset:16
	s_waitcnt vmcnt(13)
	v_pk_fma_f32 v[198:199], v[120:121], v[136:137], v[198:199]
	v_pk_fma_f32 v[196:197], v[118:119], v[134:135], v[196:197]
	global_store_dwordx4 v180, v[196:199], s[28:29] offset:512
	global_load_dwordx4 v[196:199], v183, s[4:5] offset:512
	s_waitcnt vmcnt(14)
	v_pk_fma_f32 v[202:203], v[108:109], v[132:133], v[202:203]
	v_pk_fma_f32 v[200:201], v[106:107], v[130:131], v[200:201]
	global_store_dwordx4 v180, v[200:203], s[28:29] offset:528
	global_load_dwordx4 v[200:203], v183, s[4:5] offset:528
	s_waitcnt vmcnt(15)
	v_pk_fma_f32 v[222:223], v[116:117], v[144:145], v[222:223]
	v_pk_fma_f32 v[220:221], v[114:115], v[142:143], v[220:221]
	global_store_dwordx4 v181, v[220:223], s[28:29]
	global_load_dwordx4 v[220:223], v184, s[4:5]
	s_waitcnt vmcnt(16)
	v_pk_fma_f32 v[226:227], v[112:113], v[140:141], v[226:227]
	v_pk_fma_f32 v[224:225], v[110:111], v[138:139], v[224:225]
	global_store_dwordx4 v181, v[224:227], s[28:29] offset:16
	global_load_dwordx4 v[224:227], v184, s[4:5] offset:16
	s_waitcnt vmcnt(17)
	v_pk_fma_f32 v[230:231], v[104:105], v[136:137], v[230:231]
	v_pk_fma_f32 v[228:229], v[102:103], v[134:135], v[228:229]
	global_store_dwordx4 v181, v[228:231], s[28:29] offset:512
	global_load_dwordx4 v[228:231], v184, s[4:5] offset:512
	s_waitcnt vmcnt(18)
	v_pk_fma_f32 v[234:235], v[92:93], v[132:133], v[234:235]
	v_pk_fma_f32 v[232:233], v[90:91], v[130:131], v[232:233]
	global_store_dwordx4 v181, v[232:235], s[28:29] offset:528
	global_load_dwordx4 v[232:235], v184, s[4:5] offset:528
	s_waitcnt vmcnt(19)
	v_pk_fma_f32 v[238:239], v[100:101], v[144:145], v[238:239]
	v_pk_fma_f32 v[236:237], v[98:99], v[142:143], v[236:237]
	global_store_dwordx4 v182, v[236:239], s[28:29]
	global_load_dwordx4 v[236:239], v185, s[4:5]
	s_waitcnt vmcnt(20)
	v_pk_fma_f32 v[242:243], v[96:97], v[140:141], v[242:243]
	v_pk_fma_f32 v[240:241], v[94:95], v[138:139], v[240:241]
	global_store_dwordx4 v182, v[240:243], s[28:29] offset:16
	global_load_dwordx4 v[240:243], v185, s[4:5] offset:16
	s_waitcnt vmcnt(21)
	v_pk_fma_f32 v[246:247], v[88:89], v[136:137], v[246:247]
	v_pk_fma_f32 v[244:245], v[86:87], v[134:135], v[244:245]
	global_store_dwordx4 v182, v[244:247], s[28:29] offset:512
	global_load_dwordx4 v[244:247], v185, s[4:5] offset:512
	s_waitcnt vmcnt(22)
	v_pk_fma_f32 v[250:251], v[76:77], v[132:133], v[250:251]
	v_pk_fma_f32 v[248:249], v[74:75], v[130:131], v[248:249]
	global_store_dwordx4 v182, v[248:251], s[28:29] offset:528
	global_load_dwordx4 v[248:251], v185, s[4:5] offset:528
	s_waitcnt vmcnt(22)
	v_pk_fma_f32 v[190:191], v[84:85], v[144:145], v[190:191]
	v_pk_fma_f32 v[188:189], v[82:83], v[142:143], v[188:189]
	global_store_dwordx4 v183, v[188:191], s[28:29]
	global_load_dwordx4 v[188:191], v186, s[4:5]
	s_waitcnt vmcnt(22)
	v_pk_fma_f32 v[194:195], v[80:81], v[140:141], v[194:195]
	v_pk_fma_f32 v[192:193], v[78:79], v[138:139], v[192:193]
	global_store_dwordx4 v183, v[192:195], s[28:29] offset:16
	global_load_dwordx4 v[192:195], v186, s[4:5] offset:16
	s_waitcnt vmcnt(22)
	v_pk_fma_f32 v[198:199], v[72:73], v[136:137], v[198:199]
	v_pk_fma_f32 v[196:197], v[70:71], v[134:135], v[196:197]
	global_store_dwordx4 v183, v[196:199], s[28:29] offset:512
	global_load_dwordx4 v[196:199], v186, s[4:5] offset:512
	s_waitcnt vmcnt(22)
	v_pk_fma_f32 v[202:203], v[68:69], v[132:133], v[202:203]
	v_pk_fma_f32 v[200:201], v[66:67], v[130:131], v[200:201]
	global_store_dwordx4 v183, v[200:203], s[28:29] offset:528
	global_load_dwordx4 v[200:203], v186, s[4:5] offset:528
	s_waitcnt vmcnt(22)
	v_pk_fma_f32 v[222:223], v[64:65], v[144:145], v[222:223]
	v_pk_fma_f32 v[220:221], v[62:63], v[142:143], v[220:221]
	global_store_dwordx4 v184, v[220:223], s[28:29]
	global_load_dwordx4 v[220:223], v187, s[4:5]
	s_waitcnt vmcnt(22)
	v_pk_fma_f32 v[226:227], v[60:61], v[140:141], v[226:227]
	v_pk_fma_f32 v[224:225], v[58:59], v[138:139], v[224:225]
	global_store_dwordx4 v184, v[224:227], s[28:29] offset:16
	global_load_dwordx4 v[224:227], v187, s[4:5] offset:16
	s_waitcnt vmcnt(22)
	v_pk_fma_f32 v[230:231], v[56:57], v[136:137], v[230:231]
	v_pk_fma_f32 v[228:229], v[54:55], v[134:135], v[228:229]
	global_store_dwordx4 v184, v[228:231], s[28:29] offset:512
	global_load_dwordx4 v[228:231], v187, s[4:5] offset:512
	s_waitcnt vmcnt(22)
	v_pk_fma_f32 v[234:235], v[44:45], v[132:133], v[234:235]
	v_pk_fma_f32 v[232:233], v[42:43], v[130:131], v[232:233]
	global_store_dwordx4 v184, v[232:235], s[28:29] offset:528
	global_load_dwordx4 v[232:235], v187, s[4:5] offset:528
	s_waitcnt vmcnt(22)
	v_pk_fma_f32 v[238:239], v[52:53], v[144:145], v[238:239]
	v_pk_fma_f32 v[236:237], v[50:51], v[142:143], v[236:237]
	global_store_dwordx4 v185, v[236:239], s[28:29]
	s_waitcnt vmcnt(21)
	v_pk_fma_f32 v[242:243], v[48:49], v[140:141], v[242:243]
	v_pk_fma_f32 v[240:241], v[46:47], v[138:139], v[240:241]
	global_store_dwordx4 v185, v[240:243], s[28:29] offset:16
	s_waitcnt vmcnt(20)
	v_pk_fma_f32 v[246:247], v[40:41], v[136:137], v[246:247]
	v_pk_fma_f32 v[244:245], v[38:39], v[134:135], v[244:245]
	global_store_dwordx4 v185, v[244:247], s[28:29] offset:512
	s_waitcnt vmcnt(19)
	v_pk_fma_f32 v[250:251], v[28:29], v[132:133], v[250:251]
	v_pk_fma_f32 v[248:249], v[26:27], v[130:131], v[248:249]
	global_store_dwordx4 v185, v[248:251], s[28:29] offset:528
	s_waitcnt vmcnt(18)
	v_pk_fma_f32 v[190:191], v[36:37], v[144:145], v[190:191]
	v_pk_fma_f32 v[188:189], v[34:35], v[142:143], v[188:189]
	global_store_dwordx4 v186, v[188:191], s[28:29]
	s_waitcnt vmcnt(17)
	v_pk_fma_f32 v[194:195], v[32:33], v[140:141], v[194:195]
	v_pk_fma_f32 v[192:193], v[30:31], v[138:139], v[192:193]
	global_store_dwordx4 v186, v[192:195], s[28:29] offset:16
	s_waitcnt vmcnt(16)
	v_pk_fma_f32 v[198:199], v[24:25], v[136:137], v[198:199]
	v_pk_fma_f32 v[196:197], v[22:23], v[134:135], v[196:197]
	global_store_dwordx4 v186, v[196:199], s[28:29] offset:512
	s_waitcnt vmcnt(15)
	v_pk_fma_f32 v[202:203], v[12:13], v[132:133], v[202:203]
	v_pk_fma_f32 v[200:201], v[10:11], v[130:131], v[200:201]
	global_store_dwordx4 v186, v[200:203], s[28:29] offset:528
	s_waitcnt vmcnt(14)
	v_pk_fma_f32 v[222:223], v[20:21], v[144:145], v[222:223]
	v_pk_fma_f32 v[220:221], v[18:19], v[142:143], v[220:221]
	global_store_dwordx4 v187, v[220:223], s[28:29]
	s_waitcnt vmcnt(13)
	v_pk_fma_f32 v[226:227], v[16:17], v[140:141], v[226:227]
	v_pk_fma_f32 v[224:225], v[14:15], v[138:139], v[224:225]
	global_store_dwordx4 v187, v[224:227], s[28:29] offset:16
	s_waitcnt vmcnt(12)
	v_pk_fma_f32 v[230:231], v[8:9], v[136:137], v[230:231]
	v_pk_fma_f32 v[228:229], v[6:7], v[134:135], v[228:229]
	global_store_dwordx4 v187, v[228:231], s[28:29] offset:512
	s_waitcnt vmcnt(11)
	v_pk_fma_f32 v[234:235], v[4:5], v[132:133], v[234:235]
	v_pk_fma_f32 v[232:233], v[2:3], v[130:131], v[232:233]
	global_store_dwordx4 v187, v[232:235], s[28:29] offset:528
	s_mov_b64 s[28:29], s[24:25]
	s_cbranch_vccnz .LBB0_525
